# FG epilogue conv+silu compute blocks rewritten with packed f32 math; C epilogue L2 prefetch of second-half gate rows
# speedup vs baseline: 1.0027x; 1.0027x over previous
; __device__ __forceinline__ unsigned cvt_pk_bf16(float lo, float hi) { unsigned r; asm volatile("v_cvt_pk_bf16_f32 %0, %1, %2" : "=v"(r) : "v"(lo), "v"(hi)); return r; }
; __device__ __forceinline__ float bflo(unsigned w) { return __uint_as_float(w << 16); }
; __device__ __forceinline__ float bfhi(unsigned w) { return __uint_as_float(w & 0xffff0000u); }
;     __device__ __forceinline__ void operator()(const f32x4 (&acc)[2][2][4][2], const Unit& u, int wr, int wc, int fr, int fq) const {
;     ...
;         for (int ai = 0; ai < 2; ++ai) {
;             u32x4 gv[4][2], ov[4][2];
; #pragma unroll
;             for (int m = 0; m < 4; ++m)
; #pragma unroll
;                 for (int bj = 0; bj < 2; ++bj) { const size_t r = (size_t)(row0 + ai * HALF + m * 16); const int c = col0 + bj * HALF;
;                     gv[m][bj] = *(const u32x4*)(Gt + r * N1 + c); ov[m][bj] = accum ? *(const u32x4*)(O + r * D + c) : (u32x4){0u, 0u, 0u, 0u}; }
; #pragma unroll
;             for (int m = 0; m < 4; ++m)
; #pragma unroll
;                 for (int bj = 0; bj < 2; ++bj) { const size_t r = (size_t)(row0 + ai * HALF + m * 16); const int c = col0 + bj * HALF;
;                     const u32x4 g = gv[m][bj], o0 = ov[m][bj];
;                     f32x4 v0 = acc[ai][bj][m][0], v1 = acc[ai][bj][m][1];
;                     v0[0] = v0[0] * bflo(g.x) + bflo(o0.x); v0[1] = v0[1] * bfhi(g.x) + bfhi(o0.x); v0[2] = v0[2] * bflo(g.y) + bflo(o0.y); v0[3] = v0[3] * bfhi(g.y) + bfhi(o0.y);
;                     v1[0] = v1[0] * bflo(g.z) + bflo(o0.z); v1[1] = v1[1] * bfhi(g.z) + bfhi(o0.z); v1[2] = v1[2] * bflo(g.w) + bflo(o0.w); v1[3] = v1[3] * bfhi(g.w) + bfhi(o0.w);
;                     u32x4 o; o.x = cvt_pk_bf16(v0[0], v0[1]); o.y = cvt_pk_bf16(v0[2], v0[3]); o.z = cvt_pk_bf16(v1[0], v1[1]); o.w = cvt_pk_bf16(v1[2], v1[3]);
;                     *(u32x4*)(O + r * D + c) = o; }
.LBB0_420:
	v_readlane_b32 s12, v249, 44
	v_lshl_or_b32 v128, s37, 8, v182
	v_readlane_b32 s13, v249, 45
	v_lshl_add_u32 v168, s40, 8, v180
	v_ashrrev_i32_e32 v129, 31, v128
	v_mov_b64_e32 v[170:171], s[12:13]
	v_mad_i64_i32 v[130:131], s[12:13], v168, s97, v[170:171]
	v_lshlrev_b64 v[166:167], 1, v[128:129]
	v_lshl_add_u64 v[128:129], v[130:131], 0, v[166:167]
	global_load_dwordx4 v[184:187], v[128:129], off
	global_load_dwordx4 v[152:155], v[128:129], off offset:256
	v_add_co_u32_e32 v190, vcc, 0x160000, v128
	s_nop 1
	v_addc_co_u32_e32 v191, vcc, 0, v129, vcc
	global_load_dword v188, v[190:191], off
	global_load_dword v188, v[190:191], off offset:256
	v_or_b32_e32 v128, 16, v168
	v_ashrrev_i32_e32 v129, 31, v128
	v_mad_i64_i32 v[130:131], s[12:13], v128, s97, v[170:171]
	v_lshlrev_b64 v[128:129], 11, v[128:129]
	v_lshl_add_u64 v[176:177], s[24:25], 0, v[128:129]
	v_lshl_add_u64 v[128:129], v[130:131], 0, v[166:167]
	global_load_dwordx4 v[144:147], v[128:129], off
	global_load_dwordx4 v[136:139], v[128:129], off offset:256
	v_add_co_u32_e32 v190, vcc, 0x160000, v128
	s_nop 1
	v_addc_co_u32_e32 v191, vcc, 0, v129, vcc
	global_load_dword v188, v[190:191], off
	global_load_dword v188, v[190:191], off offset:256
	v_or_b32_e32 v128, 32, v168
	v_ashrrev_i32_e32 v129, 31, v128
	v_ashrrev_i32_e32 v169, 31, v168
	v_mad_i64_i32 v[130:131], s[12:13], v128, s97, v[170:171]
	v_lshlrev_b64 v[128:129], 11, v[128:129]
	v_lshlrev_b64 v[132:133], 11, v[168:169]
	v_lshl_add_u64 v[172:173], s[24:25], 0, v[128:129]
	v_lshl_add_u64 v[128:129], v[130:131], 0, v[166:167]
	v_lshl_add_u64 v[178:179], s[24:25], 0, v[132:133]
	global_load_dwordx4 v[132:135], v[128:129], off
	v_add_co_u32_e32 v190, vcc, 0x160000, v128
	s_nop 1
	v_addc_co_u32_e32 v191, vcc, 0, v129, vcc
	global_load_dword v188, v[190:191], off
	global_load_dword v188, v[190:191], off offset:256
	s_nop 0
	global_load_dwordx4 v[128:131], v[128:129], off offset:256
	v_or_b32_e32 v140, 48, v168
	v_ashrrev_i32_e32 v141, 31, v140
	v_mad_i64_i32 v[142:143], s[12:13], v140, s97, v[170:171]
	v_lshlrev_b64 v[140:141], 11, v[140:141]
	v_lshl_add_u64 v[174:175], s[24:25], 0, v[140:141]
	v_lshl_add_u64 v[140:141], v[142:143], 0, v[166:167]
	global_load_dwordx4 v[148:151], v[140:141], off
	v_add_co_u32_e32 v190, vcc, 0x160000, v140
	s_nop 1
	v_addc_co_u32_e32 v191, vcc, 0, v141, vcc
	global_load_dword v188, v[190:191], off
	global_load_dword v188, v[190:191], off offset:256
	s_nop 0
	global_load_dwordx4 v[140:143], v[140:141], off offset:256
	s_andn2_b64 vcc, exec, s[38:39]
	s_waitcnt vmcnt(0)
	v_lshlrev_b32_e32 v169, 16, v184
	v_fma_f32 v124, v124, v169, 0
	v_and_b32_e32 v169, 0xffff0000, v184
	v_fma_f32 v125, v125, v169, 0
	v_lshlrev_b32_e32 v169, 16, v185
	v_fma_f32 v126, v126, v169, 0
	v_and_b32_e32 v169, 0xffff0000, v185
	v_fma_f32 v127, v127, v169, 0
	v_lshlrev_b32_e32 v169, 16, v186
	v_fma_f32 v169, v120, v169, 0
	v_and_b32_e32 v120, 0xffff0000, v186
	v_fma_f32 v184, v121, v120, 0
	v_lshlrev_b32_e32 v120, 16, v187
	v_fma_f32 v185, v122, v120, 0
	v_and_b32_e32 v120, 0xffff0000, v187
	v_fma_f32 v123, v123, v120, 0
	v_cvt_pk_bf16_f32 v120, v124, v125
	v_lshl_add_u64 v[124:125], v[178:179], 0, v[166:167]
	v_cvt_pk_bf16_f32 v121, v126, v127
	v_cvt_pk_bf16_f32 v122, v169, v184
	v_cvt_pk_bf16_f32 v123, v185, v123
	global_store_dwordx4 v[124:125], v[120:123], off
	s_nop 1
	v_lshlrev_b32_e32 v120, 16, v152
	v_fma_f32 v116, v116, v120, 0
	v_and_b32_e32 v120, 0xffff0000, v152
	v_fma_f32 v117, v117, v120, 0
	v_lshlrev_b32_e32 v120, 16, v153
	v_fma_f32 v118, v118, v120, 0
	v_and_b32_e32 v120, 0xffff0000, v153
	v_fma_f32 v119, v119, v120, 0
	v_lshlrev_b32_e32 v120, 16, v154
	v_fma_f32 v120, v112, v120, 0
	v_and_b32_e32 v112, 0xffff0000, v154
	v_fma_f32 v121, v113, v112, 0
	v_lshlrev_b32_e32 v112, 16, v155
	v_fma_f32 v122, v114, v112, 0
	v_and_b32_e32 v112, 0xffff0000, v155
	v_fma_f32 v115, v115, v112, 0
	v_cvt_pk_bf16_f32 v112, v116, v117
	v_cvt_pk_bf16_f32 v113, v118, v119
	v_cvt_pk_bf16_f32 v114, v120, v121
	v_cvt_pk_bf16_f32 v115, v122, v115
	global_store_dwordx4 v[124:125], v[112:115], off offset:256
	s_nop 1
	v_lshlrev_b32_e32 v112, 16, v144
	v_fma_f32 v108, v108, v112, 0
	v_and_b32_e32 v112, 0xffff0000, v144
	v_fma_f32 v109, v109, v112, 0
	v_lshlrev_b32_e32 v112, 16, v145
	v_fma_f32 v110, v110, v112, 0
	v_and_b32_e32 v112, 0xffff0000, v145
	v_fma_f32 v111, v111, v112, 0
	v_lshlrev_b32_e32 v112, 16, v146
	v_fma_f32 v112, v104, v112, 0
	v_and_b32_e32 v104, 0xffff0000, v146
	v_fma_f32 v113, v105, v104, 0
	v_lshlrev_b32_e32 v104, 16, v147
	v_fma_f32 v114, v106, v104, 0
	v_and_b32_e32 v104, 0xffff0000, v147
	v_fma_f32 v107, v107, v104, 0
	v_cvt_pk_bf16_f32 v104, v108, v109
	v_lshl_add_u64 v[108:109], v[176:177], 0, v[166:167]
	v_cvt_pk_bf16_f32 v105, v110, v111
	v_cvt_pk_bf16_f32 v106, v112, v113
	v_cvt_pk_bf16_f32 v107, v114, v107
	global_store_dwordx4 v[108:109], v[104:107], off
	s_nop 1
	v_lshlrev_b32_e32 v104, 16, v136
	v_fma_f32 v100, v100, v104, 0
	v_and_b32_e32 v104, 0xffff0000, v136
	v_fma_f32 v101, v101, v104, 0
	v_lshlrev_b32_e32 v104, 16, v137
	v_fma_f32 v102, v102, v104, 0
	v_and_b32_e32 v104, 0xffff0000, v137
	v_fma_f32 v103, v103, v104, 0
	v_lshlrev_b32_e32 v104, 16, v138
	v_fma_f32 v104, v92, v104, 0
	v_and_b32_e32 v92, 0xffff0000, v138
	v_fma_f32 v105, v93, v92, 0
	v_lshlrev_b32_e32 v92, 16, v139
	v_fma_f32 v106, v94, v92, 0
	v_and_b32_e32 v92, 0xffff0000, v139
	v_fma_f32 v95, v95, v92, 0
	v_cvt_pk_bf16_f32 v92, v100, v101
	v_cvt_pk_bf16_f32 v93, v102, v103
	v_cvt_pk_bf16_f32 v94, v104, v105
	v_cvt_pk_bf16_f32 v95, v106, v95
	global_store_dwordx4 v[108:109], v[92:95], off offset:256
	s_nop 1
; __device__ __forceinline__ unsigned cvt_pk_bf16(float lo, float hi) { unsigned r; asm volatile("v_cvt_pk_bf16_f32 %0, %1, %2" : "=v"(r) : "v"(lo), "v"(hi)); return r; }
; __device__ __forceinline__ float bflo(unsigned w) { return __uint_as_float(w << 16); }
; __device__ __forceinline__ float bfhi(unsigned w) { return __uint_as_float(w & 0xffff0000u); }
;     __device__ __forceinline__ void operator()(const f32x4 (&acc)[2][2][4][2], const Unit& u, int wr, int wc, int fr, int fq) const {
;     ...
;                 for (int bj = 0; bj < 2; ++bj) { const size_t r = (size_t)(row0 + ai * HALF + m * 16); const int c = col0 + bj * HALF;
;                     gv[m][bj] = *(const u32x4*)(Gt + r * N1 + c); ov[m][bj] = accum ? *(const u32x4*)(O + r * D + c) : (u32x4){0u, 0u, 0u, 0u}; }
; #pragma unroll
;             for (int m = 0; m < 4; ++m)
; #pragma unroll
;                 for (int bj = 0; bj < 2; ++bj) { const size_t r = (size_t)(row0 + ai * HALF + m * 16); const int c = col0 + bj * HALF;
;                     const u32x4 g = gv[m][bj], o0 = ov[m][bj];
;                     f32x4 v0 = acc[ai][bj][m][0], v1 = acc[ai][bj][m][1];
;                     v0[0] = v0[0] * bflo(g.x) + bflo(o0.x); v0[1] = v0[1] * bfhi(g.x) + bfhi(o0.x); v0[2] = v0[2] * bflo(g.y) + bflo(o0.y); v0[3] = v0[3] * bfhi(g.y) + bfhi(o0.y);
;                     v1[0] = v1[0] * bflo(g.z) + bflo(o0.z); v1[1] = v1[1] * bfhi(g.z) + bfhi(o0.z); v1[2] = v1[2] * bflo(g.w) + bflo(o0.w); v1[3] = v1[3] * bfhi(g.w) + bfhi(o0.w);
;                     u32x4 o; o.x = cvt_pk_bf16(v0[0], v0[1]); o.y = cvt_pk_bf16(v0[2], v0[3]); o.z = cvt_pk_bf16(v1[0], v1[1]); o.w = cvt_pk_bf16(v1[2], v1[3]);
;                     *(u32x4*)(O + r * D + c) = o; }
	v_lshlrev_b32_e32 v92, 16, v132
	v_fma_f32 v92, v96, v92, 0
	v_lshlrev_b32_e32 v96, 16, v134
	v_and_b32_e32 v93, 0xffff0000, v132
	v_fma_f32 v96, v88, v96, 0
	v_and_b32_e32 v88, 0xffff0000, v134
	v_fma_f32 v93, v97, v93, 0
	v_lshlrev_b32_e32 v94, 16, v133
	v_fma_f32 v97, v89, v88, 0
	v_lshlrev_b32_e32 v88, 16, v135
	v_fma_f32 v94, v98, v94, 0
	v_fma_f32 v98, v90, v88, 0
	v_and_b32_e32 v88, 0xffff0000, v135
	v_and_b32_e32 v95, 0xffff0000, v133
	v_fma_f32 v91, v91, v88, 0
	v_cvt_pk_bf16_f32 v88, v92, v93
	v_lshl_add_u64 v[92:93], v[172:173], 0, v[166:167]
	v_fma_f32 v95, v99, v95, 0
	v_cvt_pk_bf16_f32 v89, v94, v95
	v_cvt_pk_bf16_f32 v90, v96, v97
	v_cvt_pk_bf16_f32 v91, v98, v91
	global_store_dwordx4 v[92:93], v[88:91], off
	s_nop 1
	v_lshlrev_b32_e32 v88, 16, v128
	v_fma_f32 v84, v84, v88, 0
	v_and_b32_e32 v88, 0xffff0000, v128
	v_fma_f32 v85, v85, v88, 0
	v_lshlrev_b32_e32 v88, 16, v129
	v_fma_f32 v86, v86, v88, 0
	v_and_b32_e32 v88, 0xffff0000, v129
	v_fma_f32 v87, v87, v88, 0
	v_lshlrev_b32_e32 v88, 16, v130
	v_fma_f32 v88, v76, v88, 0
	v_and_b32_e32 v76, 0xffff0000, v130
	v_fma_f32 v89, v77, v76, 0
	v_lshlrev_b32_e32 v76, 16, v131
	v_fma_f32 v90, v78, v76, 0
	v_and_b32_e32 v76, 0xffff0000, v131
	v_fma_f32 v79, v79, v76, 0
	v_cvt_pk_bf16_f32 v76, v84, v85
	v_cvt_pk_bf16_f32 v77, v86, v87
	v_cvt_pk_bf16_f32 v78, v88, v89
	v_cvt_pk_bf16_f32 v79, v90, v79
	global_store_dwordx4 v[92:93], v[76:79], off offset:256
	v_add_u32_e32 v88, 0xb0, v168
	v_ashrrev_i32_e32 v89, 31, v88
	v_lshlrev_b32_e32 v76, 16, v148
	v_fma_f32 v76, v80, v76, 0
	v_lshlrev_b32_e32 v80, 16, v150
	v_and_b32_e32 v77, 0xffff0000, v148
	v_fma_f32 v80, v72, v80, 0
	v_and_b32_e32 v72, 0xffff0000, v150
	v_fma_f32 v77, v81, v77, 0
	v_lshlrev_b32_e32 v78, 16, v149
	v_fma_f32 v81, v73, v72, 0
	v_lshlrev_b32_e32 v72, 16, v151
	v_fma_f32 v78, v82, v78, 0
	v_fma_f32 v82, v74, v72, 0
	v_and_b32_e32 v72, 0xffff0000, v151
	v_and_b32_e32 v79, 0xffff0000, v149
	v_fma_f32 v75, v75, v72, 0
	v_cvt_pk_bf16_f32 v72, v76, v77
	v_lshl_add_u64 v[76:77], v[174:175], 0, v[166:167]
	v_fma_f32 v79, v83, v79, 0
	v_cvt_pk_bf16_f32 v73, v78, v79
	v_cvt_pk_bf16_f32 v74, v80, v81
	v_cvt_pk_bf16_f32 v75, v82, v75
	global_store_dwordx4 v[76:77], v[72:75], off
	v_add_u32_e32 v80, 0xa0, v168
	v_ashrrev_i32_e32 v81, 31, v80
	v_lshlrev_b32_e32 v72, 16, v140
	v_fma_f32 v68, v68, v72, 0
	v_and_b32_e32 v72, 0xffff0000, v140
	v_fma_f32 v69, v69, v72, 0
	v_lshlrev_b32_e32 v72, 16, v141
	v_fma_f32 v70, v70, v72, 0
	v_and_b32_e32 v72, 0xffff0000, v141
	v_fma_f32 v71, v71, v72, 0
	v_lshlrev_b32_e32 v72, 16, v142
	v_fma_f32 v72, v64, v72, 0
	v_and_b32_e32 v64, 0xffff0000, v142
	v_fma_f32 v73, v65, v64, 0
	v_lshlrev_b32_e32 v64, 16, v143
	v_fma_f32 v74, v66, v64, 0
	v_and_b32_e32 v64, 0xffff0000, v143
	v_fma_f32 v67, v67, v64, 0
	v_cvt_pk_bf16_f32 v64, v68, v69
	v_cvt_pk_bf16_f32 v65, v70, v71
	v_cvt_pk_bf16_f32 v66, v72, v73
	v_cvt_pk_bf16_f32 v67, v74, v67
	global_store_dwordx4 v[76:77], v[64:67], off offset:256
	v_add_u32_e32 v72, 0x90, v168
	v_ashrrev_i32_e32 v73, 31, v72
	v_add_u32_e32 v64, 0x80, v168
	v_ashrrev_i32_e32 v65, 31, v64
	v_mad_i64_i32 v[66:67], s[12:13], v64, s97, v[170:171]
	v_lshlrev_b64 v[64:65], 11, v[64:65]
	v_lshl_add_u64 v[68:69], v[66:67], 0, v[166:167]
	v_lshl_add_u64 v[96:97], s[24:25], 0, v[64:65]
	global_load_dwordx4 v[64:67], v[68:69], off
	s_nop 0
	global_load_dwordx4 v[68:71], v[68:69], off offset:256
	v_mad_i64_i32 v[74:75], s[12:13], v72, s97, v[170:171]
	v_lshlrev_b64 v[72:73], 11, v[72:73]
	v_lshl_add_u64 v[76:77], v[74:75], 0, v[166:167]
	v_lshl_add_u64 v[98:99], s[24:25], 0, v[72:73]
	global_load_dwordx4 v[72:75], v[76:77], off
	s_nop 0
	global_load_dwordx4 v[76:79], v[76:77], off offset:256
	v_mad_i64_i32 v[82:83], s[12:13], v80, s97, v[170:171]
	v_lshlrev_b64 v[80:81], 11, v[80:81]
	v_lshl_add_u64 v[84:85], v[82:83], 0, v[166:167]
	v_lshl_add_u64 v[100:101], s[24:25], 0, v[80:81]
	global_load_dwordx4 v[80:83], v[84:85], off
	s_nop 0
	global_load_dwordx4 v[84:87], v[84:85], off offset:256
	v_mad_i64_i32 v[90:91], s[12:13], v88, s97, v[170:171]
	v_lshlrev_b64 v[88:89], 11, v[88:89]
	v_lshl_add_u64 v[92:93], v[90:91], 0, v[166:167]
	v_lshl_add_u64 v[102:103], s[24:25], 0, v[88:89]
	global_load_dwordx4 v[88:91], v[92:93], off
	s_nop 0
	global_load_dwordx4 v[92:95], v[92:93], off offset:256
	s_mov_b64 s[12:13], -1
	s_waitcnt vmcnt(7)
	v_lshlrev_b32_e32 v104, 16, v64
	v_and_b32_e32 v64, 0xffff0000, v64
	v_fma_f32 v61, v61, v64, 0
	v_lshlrev_b32_e32 v64, 16, v65
	v_fma_f32 v62, v62, v64, 0
	v_and_b32_e32 v64, 0xffff0000, v65
	v_fma_f32 v63, v63, v64, 0
	v_lshlrev_b32_e32 v64, 16, v66
	v_fma_f32 v64, v56, v64, 0
	v_and_b32_e32 v56, 0xffff0000, v66
	v_fma_f32 v65, v57, v56, 0
	v_lshlrev_b32_e32 v56, 16, v67
	v_fma_f32 v60, v60, v104, 0
	v_fma_f32 v66, v58, v56, 0
	v_and_b32_e32 v56, 0xffff0000, v67
	v_fma_f32 v59, v59, v56, 0
	v_cvt_pk_bf16_f32 v56, v60, v61
	v_lshl_add_u64 v[60:61], v[96:97], 0, v[166:167]
	v_cvt_pk_bf16_f32 v57, v62, v63
	v_cvt_pk_bf16_f32 v58, v64, v65
	v_cvt_pk_bf16_f32 v59, v66, v59
	global_store_dwordx4 v[60:61], v[56:59], off
	s_waitcnt vmcnt(7)
; __device__ __forceinline__ unsigned cvt_pk_bf16(float lo, float hi) { unsigned r; asm volatile("v_cvt_pk_bf16_f32 %0, %1, %2" : "=v"(r) : "v"(lo), "v"(hi)); return r; }
; __device__ __forceinline__ float bflo(unsigned w) { return __uint_as_float(w << 16); }
; __device__ __forceinline__ float bfhi(unsigned w) { return __uint_as_float(w & 0xffff0000u); }
;     __device__ __forceinline__ void operator()(const f32x4 (&acc)[2][2][4][2], const Unit& u, int wr, int wc, int fr, int fq) const {
;     ...
;             for (int m = 0; m < 4; ++m)
; #pragma unroll
;                 for (int bj = 0; bj < 2; ++bj) { const size_t r = (size_t)(row0 + ai * HALF + m * 16); const int c = col0 + bj * HALF;
;                     const u32x4 g = gv[m][bj], o0 = ov[m][bj];
;                     f32x4 v0 = acc[ai][bj][m][0], v1 = acc[ai][bj][m][1];
;                     v0[0] = v0[0] * bflo(g.x) + bflo(o0.x); v0[1] = v0[1] * bfhi(g.x) + bfhi(o0.x); v0[2] = v0[2] * bflo(g.y) + bflo(o0.y); v0[3] = v0[3] * bfhi(g.y) + bfhi(o0.y);
;                     v1[0] = v1[0] * bflo(g.z) + bflo(o0.z); v1[1] = v1[1] * bfhi(g.z) + bfhi(o0.z); v1[2] = v1[2] * bflo(g.w) + bflo(o0.w); v1[3] = v1[3] * bfhi(g.w) + bfhi(o0.w);
;                     u32x4 o; o.x = cvt_pk_bf16(v0[0], v0[1]); o.y = cvt_pk_bf16(v0[2], v0[3]); o.z = cvt_pk_bf16(v1[0], v1[1]); o.w = cvt_pk_bf16(v1[2], v1[3]);
;                     *(u32x4*)(O + r * D + c) = o; }
	s_nop 0
	v_lshlrev_b32_e32 v56, 16, v68
	v_fma_f32 v52, v52, v56, 0
	v_and_b32_e32 v56, 0xffff0000, v68
	v_fma_f32 v53, v53, v56, 0
	v_lshlrev_b32_e32 v56, 16, v69
	v_fma_f32 v54, v54, v56, 0
	v_and_b32_e32 v56, 0xffff0000, v69
	v_fma_f32 v55, v55, v56, 0
	v_lshlrev_b32_e32 v56, 16, v70
	v_fma_f32 v56, v44, v56, 0
	v_and_b32_e32 v44, 0xffff0000, v70
	v_fma_f32 v57, v45, v44, 0
	v_lshlrev_b32_e32 v44, 16, v71
	v_fma_f32 v58, v46, v44, 0
	v_and_b32_e32 v44, 0xffff0000, v71
	v_fma_f32 v47, v47, v44, 0
	v_cvt_pk_bf16_f32 v44, v52, v53
	v_cvt_pk_bf16_f32 v45, v54, v55
	v_cvt_pk_bf16_f32 v46, v56, v57
	v_cvt_pk_bf16_f32 v47, v58, v47
	global_store_dwordx4 v[60:61], v[44:47], off offset:256
	s_waitcnt vmcnt(7)
	s_nop 0
	v_lshlrev_b32_e32 v44, 16, v72
	v_fma_f32 v44, v48, v44, 0
	v_lshlrev_b32_e32 v48, 16, v74
	v_and_b32_e32 v45, 0xffff0000, v72
	v_fma_f32 v48, v40, v48, 0
	v_and_b32_e32 v40, 0xffff0000, v74
	v_fma_f32 v45, v49, v45, 0
	v_lshlrev_b32_e32 v46, 16, v73
	v_fma_f32 v49, v41, v40, 0
	v_lshlrev_b32_e32 v40, 16, v75
	v_fma_f32 v46, v50, v46, 0
	v_fma_f32 v50, v42, v40, 0
	v_and_b32_e32 v40, 0xffff0000, v75
	v_and_b32_e32 v47, 0xffff0000, v73
	v_fma_f32 v43, v43, v40, 0
	v_cvt_pk_bf16_f32 v40, v44, v45
	v_lshl_add_u64 v[44:45], v[98:99], 0, v[166:167]
	v_fma_f32 v47, v51, v47, 0
	v_cvt_pk_bf16_f32 v41, v46, v47
	v_cvt_pk_bf16_f32 v42, v48, v49
	v_cvt_pk_bf16_f32 v43, v50, v43
	global_store_dwordx4 v[44:45], v[40:43], off
	s_waitcnt vmcnt(7)
	s_nop 0
	v_lshlrev_b32_e32 v40, 16, v76
	v_fma_f32 v36, v36, v40, 0
	v_and_b32_e32 v40, 0xffff0000, v76
	v_fma_f32 v37, v37, v40, 0
	v_lshlrev_b32_e32 v40, 16, v77
	v_fma_f32 v38, v38, v40, 0
	v_and_b32_e32 v40, 0xffff0000, v77
	v_fma_f32 v39, v39, v40, 0
	v_lshlrev_b32_e32 v40, 16, v78
	v_fma_f32 v40, v28, v40, 0
	v_and_b32_e32 v28, 0xffff0000, v78
	v_fma_f32 v41, v29, v28, 0
	v_lshlrev_b32_e32 v28, 16, v79
	v_fma_f32 v42, v30, v28, 0
	v_and_b32_e32 v28, 0xffff0000, v79
	v_fma_f32 v31, v31, v28, 0
	v_cvt_pk_bf16_f32 v28, v36, v37
	v_cvt_pk_bf16_f32 v29, v38, v39
	v_cvt_pk_bf16_f32 v30, v40, v41
	v_cvt_pk_bf16_f32 v31, v42, v31
	global_store_dwordx4 v[44:45], v[28:31], off offset:256
	s_waitcnt vmcnt(7)
	s_nop 0
	v_lshlrev_b32_e32 v28, 16, v80
	v_fma_f32 v28, v32, v28, 0
	v_lshlrev_b32_e32 v32, 16, v82
	v_and_b32_e32 v29, 0xffff0000, v80
	v_fma_f32 v32, v24, v32, 0
	v_and_b32_e32 v24, 0xffff0000, v82
	v_fma_f32 v29, v33, v29, 0
	v_lshlrev_b32_e32 v30, 16, v81
	v_fma_f32 v33, v25, v24, 0
	v_lshlrev_b32_e32 v24, 16, v83
	v_fma_f32 v30, v34, v30, 0
	v_fma_f32 v34, v26, v24, 0
	v_and_b32_e32 v24, 0xffff0000, v83
	v_and_b32_e32 v31, 0xffff0000, v81
	v_fma_f32 v27, v27, v24, 0
	v_cvt_pk_bf16_f32 v24, v28, v29
	v_lshl_add_u64 v[28:29], v[100:101], 0, v[166:167]
	v_fma_f32 v31, v35, v31, 0
	v_cvt_pk_bf16_f32 v25, v30, v31
	v_cvt_pk_bf16_f32 v26, v32, v33
	v_cvt_pk_bf16_f32 v27, v34, v27
	global_store_dwordx4 v[28:29], v[24:27], off
	s_waitcnt vmcnt(7)
	s_nop 0
	v_lshlrev_b32_e32 v24, 16, v84
	v_fma_f32 v20, v20, v24, 0
	v_and_b32_e32 v24, 0xffff0000, v84
	v_fma_f32 v21, v21, v24, 0
	v_lshlrev_b32_e32 v24, 16, v85
	v_fma_f32 v22, v22, v24, 0
	v_and_b32_e32 v24, 0xffff0000, v85
	v_fma_f32 v23, v23, v24, 0
	v_lshlrev_b32_e32 v24, 16, v86
	v_fma_f32 v24, v12, v24, 0
	v_and_b32_e32 v12, 0xffff0000, v86
	v_fma_f32 v25, v13, v12, 0
	v_lshlrev_b32_e32 v12, 16, v87
	v_fma_f32 v26, v14, v12, 0
	v_and_b32_e32 v12, 0xffff0000, v87
	v_fma_f32 v15, v15, v12, 0
	v_cvt_pk_bf16_f32 v12, v20, v21
	v_cvt_pk_bf16_f32 v13, v22, v23
	v_cvt_pk_bf16_f32 v14, v24, v25
	v_cvt_pk_bf16_f32 v15, v26, v15
	global_store_dwordx4 v[28:29], v[12:15], off offset:256
	s_waitcnt vmcnt(7)
	s_nop 0
	v_lshlrev_b32_e32 v12, 16, v88
	v_fma_f32 v12, v16, v12, 0
	v_lshlrev_b32_e32 v16, 16, v90
	v_and_b32_e32 v13, 0xffff0000, v88
	v_fma_f32 v16, v8, v16, 0
	v_and_b32_e32 v8, 0xffff0000, v90
	v_fma_f32 v13, v17, v13, 0
	v_lshlrev_b32_e32 v14, 16, v89
	v_fma_f32 v17, v9, v8, 0
	v_lshlrev_b32_e32 v8, 16, v91
	v_fma_f32 v14, v18, v14, 0
	v_fma_f32 v18, v10, v8, 0
	v_and_b32_e32 v8, 0xffff0000, v91
	v_and_b32_e32 v15, 0xffff0000, v89
	v_fma_f32 v11, v11, v8, 0
	v_cvt_pk_bf16_f32 v8, v12, v13
	v_lshl_add_u64 v[12:13], v[102:103], 0, v[166:167]
	v_fma_f32 v15, v19, v15, 0
	v_cvt_pk_bf16_f32 v9, v14, v15
	v_cvt_pk_bf16_f32 v10, v16, v17
	v_cvt_pk_bf16_f32 v11, v18, v11
	global_store_dwordx4 v[12:13], v[8:11], off
	s_waitcnt vmcnt(7)
	s_nop 0
	v_lshlrev_b32_e32 v8, 16, v92
	v_fma_f32 v4, v4, v8, 0
	v_and_b32_e32 v8, 0xffff0000, v92
	v_fma_f32 v5, v5, v8, 0
	v_lshlrev_b32_e32 v8, 16, v93
	v_fma_f32 v6, v6, v8, 0
	v_and_b32_e32 v8, 0xffff0000, v93
	v_fma_f32 v7, v7, v8, 0
	v_lshlrev_b32_e32 v8, 16, v94
	v_fma_f32 v8, v0, v8, 0
	v_and_b32_e32 v0, 0xffff0000, v94
	v_fma_f32 v9, v1, v0, 0
	v_lshlrev_b32_e32 v0, 16, v95
	v_fma_f32 v10, v2, v0, 0
	v_and_b32_e32 v0, 0xffff0000, v95
	v_fma_f32 v3, v3, v0, 0
	v_cvt_pk_bf16_f32 v0, v4, v5
	v_cvt_pk_bf16_f32 v1, v6, v7
	v_cvt_pk_bf16_f32 v2, v8, v9
	v_cvt_pk_bf16_f32 v3, v10, v3
	global_store_dwordx4 v[12:13], v[0:3], off offset:256
	s_cbranch_vccnz .LBB0_409
	s_andn2_b64 vcc, exec, s[0:1]
	s_cbranch_vccnz .LBB0_408
	s_barrier
	s_branch .LBB0_408

; __device__ __forceinline__ unsigned cvt_pk_bf16(float lo, float hi) { unsigned r; asm volatile("v_cvt_pk_bf16_f32 %0, %1, %2" : "=v"(r) : "v"(lo), "v"(hi)); return r; }
; __device__ __forceinline__ float bflo(unsigned w) { return __uint_as_float(w << 16); }
; __device__ __forceinline__ float bfhi(unsigned w) { return __uint_as_float(w & 0xffff0000u); }
;     __device__ __forceinline__ void operator()(const f32x4 (&acc)[2][2][4][2], const Unit& u, int wr, int wc, int fr, int fq) const {
;     ...
;         for (int ai = 0; ai < 2; ++ai) {
;             u32x4 gv[4][2], ov[4][2];
; #pragma unroll
;             for (int m = 0; m < 4; ++m)
; #pragma unroll
;                 for (int bj = 0; bj < 2; ++bj) { const size_t r = (size_t)(row0 + ai * HALF + m * 16); const int c = col0 + bj * HALF;
;                     gv[m][bj] = *(const u32x4*)(Gt + r * N1 + c); ov[m][bj] = accum ? *(const u32x4*)(O + r * D + c) : (u32x4){0u, 0u, 0u, 0u}; }
; #pragma unroll
;             for (int m = 0; m < 4; ++m)
; #pragma unroll
;                 for (int bj = 0; bj < 2; ++bj) { const size_t r = (size_t)(row0 + ai * HALF + m * 16); const int c = col0 + bj * HALF;
;                     const u32x4 g = gv[m][bj], o0 = ov[m][bj];
;                     f32x4 v0 = acc[ai][bj][m][0], v1 = acc[ai][bj][m][1];
;                     v0[0] = v0[0] * bflo(g.x) + bflo(o0.x); v0[1] = v0[1] * bfhi(g.x) + bfhi(o0.x); v0[2] = v0[2] * bflo(g.y) + bflo(o0.y); v0[3] = v0[3] * bfhi(g.y) + bfhi(o0.y);
;                     v1[0] = v1[0] * bflo(g.z) + bflo(o0.z); v1[1] = v1[1] * bfhi(g.z) + bfhi(o0.z); v1[2] = v1[2] * bflo(g.w) + bflo(o0.w); v1[3] = v1[3] * bfhi(g.w) + bfhi(o0.w);
;                     u32x4 o; o.x = cvt_pk_bf16(v0[0], v0[1]); o.y = cvt_pk_bf16(v0[2], v0[3]); o.z = cvt_pk_bf16(v1[0], v1[1]); o.w = cvt_pk_bf16(v1[2], v1[3]);
;                     *(u32x4*)(O + r * D + c) = o; }
.LBB0_440:
	v_readlane_b32 s12, v249, 48
	v_lshl_or_b32 v128, s37, 8, v230
	v_readlane_b32 s13, v249, 49
	v_lshl_add_u32 v206, s40, 8, v228
	v_ashrrev_i32_e32 v129, 31, v128
	v_mov_b64_e32 v[208:209], s[12:13]
	v_ashrrev_i32_e32 v207, 31, v206
	v_mad_i64_i32 v[130:131], s[12:13], v206, s97, v[208:209]
	v_lshlrev_b64 v[210:211], 1, v[128:129]
	v_lshlrev_b64 v[132:133], 11, v[206:207]
	v_lshl_add_u64 v[128:129], v[130:131], 0, v[210:211]
	v_lshl_add_u64 v[132:133], s[24:25], 0, v[132:133]
	global_load_dwordx4 v[184:187], v[128:129], off
	v_lshl_add_u64 v[218:219], v[132:133], 0, v[210:211]
	global_load_dwordx4 v[188:191], v[218:219], off
	global_load_dwordx4 v[176:179], v[128:129], off offset:256
	global_load_dwordx4 v[180:183], v[218:219], off offset:256
	v_add_co_u32_e32 v164, vcc, 0x160000, v128
	s_nop 1
	v_addc_co_u32_e32 v165, vcc, 0, v129, vcc
	global_load_dword v166, v[164:165], off
	global_load_dword v166, v[164:165], off offset:256
	v_add_co_u32_e32 v164, vcc, 0x40000, v218
	s_nop 1
	v_addc_co_u32_e32 v165, vcc, 0, v219, vcc
	global_load_dword v166, v[164:165], off
	global_load_dword v166, v[164:165], off offset:256
	v_or_b32_e32 v128, 16, v206
	v_ashrrev_i32_e32 v129, 31, v128
	v_mad_i64_i32 v[130:131], s[12:13], v128, s97, v[208:209]
	v_lshlrev_b64 v[128:129], 11, v[128:129]
	v_lshl_add_u64 v[130:131], v[130:131], 0, v[210:211]
	v_lshl_add_u64 v[128:129], s[24:25], 0, v[128:129]
	global_load_dwordx4 v[156:159], v[130:131], off
	v_lshl_add_u64 v[214:215], v[128:129], 0, v[210:211]
	global_load_dwordx4 v[160:163], v[214:215], off
	global_load_dwordx4 v[136:139], v[130:131], off offset:256
	global_load_dwordx4 v[140:143], v[214:215], off offset:256
	v_add_co_u32_e32 v164, vcc, 0x160000, v130
	s_nop 1
	v_addc_co_u32_e32 v165, vcc, 0, v131, vcc
	global_load_dword v166, v[164:165], off
	global_load_dword v166, v[164:165], off offset:256
	v_add_co_u32_e32 v164, vcc, 0x40000, v214
	s_nop 1
	v_addc_co_u32_e32 v165, vcc, 0, v215, vcc
	global_load_dword v166, v[164:165], off
	global_load_dword v166, v[164:165], off offset:256
	v_or_b32_e32 v128, 32, v206
	v_ashrrev_i32_e32 v129, 31, v128
	v_mad_i64_i32 v[130:131], s[12:13], v128, s97, v[208:209]
	v_lshlrev_b64 v[128:129], 11, v[128:129]
	v_lshl_add_u64 v[130:131], v[130:131], 0, v[210:211]
	v_lshl_add_u64 v[128:129], s[24:25], 0, v[128:129]
	global_load_dwordx4 v[144:147], v[130:131], off
	v_lshl_add_u64 v[212:213], v[128:129], 0, v[210:211]
	global_load_dwordx4 v[148:151], v[212:213], off
	v_add_co_u32_e32 v164, vcc, 0x160000, v130
	s_nop 1
	v_addc_co_u32_e32 v165, vcc, 0, v131, vcc
	global_load_dword v166, v[164:165], off
	global_load_dword v166, v[164:165], off offset:256
	v_add_co_u32_e32 v164, vcc, 0x40000, v212
	s_nop 1
	v_addc_co_u32_e32 v165, vcc, 0, v213, vcc
	global_load_dword v166, v[164:165], off
	global_load_dword v166, v[164:165], off offset:256
	s_nop 0
	global_load_dwordx4 v[128:131], v[130:131], off offset:256
	s_nop 0
	global_load_dwordx4 v[132:135], v[212:213], off offset:256
	v_or_b32_e32 v152, 48, v206
	v_ashrrev_i32_e32 v153, 31, v152
	v_mad_i64_i32 v[154:155], s[12:13], v152, s97, v[208:209]
	v_lshlrev_b64 v[152:153], 11, v[152:153]
	v_lshl_add_u64 v[154:155], v[154:155], 0, v[210:211]
	v_lshl_add_u64 v[152:153], s[24:25], 0, v[152:153]
	global_load_dwordx4 v[168:171], v[154:155], off
	v_lshl_add_u64 v[216:217], v[152:153], 0, v[210:211]
	global_load_dwordx4 v[172:175], v[216:217], off
	v_add_co_u32_e32 v164, vcc, 0x160000, v154
	s_nop 1
	v_addc_co_u32_e32 v165, vcc, 0, v155, vcc
	global_load_dword v166, v[164:165], off
	global_load_dword v166, v[164:165], off offset:256
	v_add_co_u32_e32 v164, vcc, 0x40000, v216
	s_nop 1
	v_addc_co_u32_e32 v165, vcc, 0, v217, vcc
	global_load_dword v166, v[164:165], off
	global_load_dword v166, v[164:165], off offset:256
	s_nop 0
	global_load_dwordx4 v[152:155], v[154:155], off offset:256
	s_nop 0
	global_load_dwordx4 v[164:167], v[216:217], off offset:256
	s_andn2_b64 vcc, exec, s[38:39]
	s_waitcnt vmcnt(0)
	v_lshlrev_b32_e32 v232, 16, v188
	v_lshlrev_b32_e32 v207, 16, v184
	v_fmac_f32_e32 v232, v124, v207
	v_and_b32_e32 v124, 0xffff0000, v184
	v_and_b32_e32 v184, 0xffff0000, v188
	v_fmac_f32_e32 v184, v125, v124
	v_lshlrev_b32_e32 v124, 16, v185
	v_lshlrev_b32_e32 v125, 16, v189
	v_fmac_f32_e32 v125, v126, v124
	v_and_b32_e32 v124, 0xffff0000, v185
	v_and_b32_e32 v126, 0xffff0000, v189
	v_fmac_f32_e32 v126, v127, v124
	v_lshlrev_b32_e32 v124, 16, v186
	v_lshlrev_b32_e32 v127, 16, v190
	v_fmac_f32_e32 v127, v120, v124
	v_and_b32_e32 v120, 0xffff0000, v186
	v_and_b32_e32 v124, 0xffff0000, v190
	v_fmac_f32_e32 v124, v121, v120
	v_lshlrev_b32_e32 v120, 16, v187
	v_lshlrev_b32_e32 v185, 16, v191
	v_fmac_f32_e32 v185, v122, v120
	v_and_b32_e32 v120, 0xffff0000, v187
	v_and_b32_e32 v186, 0xffff0000, v191
	v_fmac_f32_e32 v186, v123, v120
	v_cvt_pk_bf16_f32 v120, v232, v184
	v_cvt_pk_bf16_f32 v121, v125, v126
	v_cvt_pk_bf16_f32 v122, v127, v124
	v_cvt_pk_bf16_f32 v123, v185, v186
	global_store_dwordx4 v[218:219], v[120:123], off
	s_nop 1
	v_lshlrev_b32_e32 v120, 16, v176
	v_lshlrev_b32_e32 v121, 16, v180
	v_fmac_f32_e32 v121, v116, v120
	v_and_b32_e32 v116, 0xffff0000, v176
	v_and_b32_e32 v120, 0xffff0000, v180
	v_fmac_f32_e32 v120, v117, v116
	v_lshlrev_b32_e32 v116, 16, v177
	v_lshlrev_b32_e32 v117, 16, v181
	v_fmac_f32_e32 v117, v118, v116
	v_and_b32_e32 v116, 0xffff0000, v177
	v_and_b32_e32 v118, 0xffff0000, v181
	v_fmac_f32_e32 v118, v119, v116
	v_lshlrev_b32_e32 v116, 16, v178
	v_lshlrev_b32_e32 v119, 16, v182
	v_fmac_f32_e32 v119, v108, v116
	v_and_b32_e32 v108, 0xffff0000, v178
	v_and_b32_e32 v116, 0xffff0000, v182
; __device__ __forceinline__ unsigned cvt_pk_bf16(float lo, float hi) { unsigned r; asm volatile("v_cvt_pk_bf16_f32 %0, %1, %2" : "=v"(r) : "v"(lo), "v"(hi)); return r; }
; __device__ __forceinline__ float bflo(unsigned w) { return __uint_as_float(w << 16); }
; __device__ __forceinline__ float bfhi(unsigned w) { return __uint_as_float(w & 0xffff0000u); }
;     __device__ __forceinline__ void operator()(const f32x4 (&acc)[2][2][4][2], const Unit& u, int wr, int wc, int fr, int fq) const {
;     ...
;             for (int m = 0; m < 4; ++m)
; #pragma unroll
;                 for (int bj = 0; bj < 2; ++bj) { const size_t r = (size_t)(row0 + ai * HALF + m * 16); const int c = col0 + bj * HALF;
;                     const u32x4 g = gv[m][bj], o0 = ov[m][bj];
;                     f32x4 v0 = acc[ai][bj][m][0], v1 = acc[ai][bj][m][1];
;                     v0[0] = v0[0] * bflo(g.x) + bflo(o0.x); v0[1] = v0[1] * bfhi(g.x) + bfhi(o0.x); v0[2] = v0[2] * bflo(g.y) + bflo(o0.y); v0[3] = v0[3] * bfhi(g.y) + bfhi(o0.y);
;                     v1[0] = v1[0] * bflo(g.z) + bflo(o0.z); v1[1] = v1[1] * bfhi(g.z) + bfhi(o0.z); v1[2] = v1[2] * bflo(g.w) + bflo(o0.w); v1[3] = v1[3] * bfhi(g.w) + bfhi(o0.w);
;                     u32x4 o; o.x = cvt_pk_bf16(v0[0], v0[1]); o.y = cvt_pk_bf16(v0[2], v0[3]); o.z = cvt_pk_bf16(v1[0], v1[1]); o.w = cvt_pk_bf16(v1[2], v1[3]);
;                     *(u32x4*)(O + r * D + c) = o; }
	v_fmac_f32_e32 v116, v109, v108
	v_lshlrev_b32_e32 v108, 16, v179
	v_lshlrev_b32_e32 v122, 16, v183
	v_fmac_f32_e32 v122, v110, v108
	v_and_b32_e32 v108, 0xffff0000, v179
	v_and_b32_e32 v123, 0xffff0000, v183
	v_fmac_f32_e32 v123, v111, v108
	v_cvt_pk_bf16_f32 v108, v121, v120
	v_cvt_pk_bf16_f32 v109, v117, v118
	v_cvt_pk_bf16_f32 v110, v119, v116
	v_cvt_pk_bf16_f32 v111, v122, v123
	global_store_dwordx4 v[218:219], v[108:111], off offset:256
	s_nop 1
	v_lshlrev_b32_e32 v108, 16, v156
	v_lshlrev_b32_e32 v109, 16, v160
	v_fmac_f32_e32 v109, v112, v108
	v_and_b32_e32 v108, 0xffff0000, v156
	v_and_b32_e32 v110, 0xffff0000, v160
	v_fmac_f32_e32 v110, v113, v108
	v_lshlrev_b32_e32 v108, 16, v157
	v_lshlrev_b32_e32 v111, 16, v161
	v_fmac_f32_e32 v111, v114, v108
	v_and_b32_e32 v108, 0xffff0000, v157
	v_and_b32_e32 v112, 0xffff0000, v161
	v_fmac_f32_e32 v112, v115, v108
	v_lshlrev_b32_e32 v108, 16, v158
	v_lshlrev_b32_e32 v113, 16, v162
	v_fmac_f32_e32 v113, v104, v108
	v_and_b32_e32 v104, 0xffff0000, v158
	v_and_b32_e32 v108, 0xffff0000, v162
	v_fmac_f32_e32 v108, v105, v104
	v_lshlrev_b32_e32 v104, 16, v159
	v_lshlrev_b32_e32 v114, 16, v163
	v_fmac_f32_e32 v114, v106, v104
	v_and_b32_e32 v104, 0xffff0000, v159
	v_and_b32_e32 v115, 0xffff0000, v163
	v_fmac_f32_e32 v115, v107, v104
	v_cvt_pk_bf16_f32 v104, v109, v110
	v_cvt_pk_bf16_f32 v105, v111, v112
	v_cvt_pk_bf16_f32 v106, v113, v108
	v_cvt_pk_bf16_f32 v107, v114, v115
	global_store_dwordx4 v[214:215], v[104:107], off
	s_nop 1
	v_lshlrev_b32_e32 v104, 16, v136
	v_lshlrev_b32_e32 v105, 16, v140
	v_fmac_f32_e32 v105, v100, v104
	v_and_b32_e32 v100, 0xffff0000, v136
	v_and_b32_e32 v104, 0xffff0000, v140
	v_fmac_f32_e32 v104, v101, v100
	v_lshlrev_b32_e32 v100, 16, v137
	v_lshlrev_b32_e32 v101, 16, v141
	v_fmac_f32_e32 v101, v102, v100
	v_and_b32_e32 v100, 0xffff0000, v137
	v_and_b32_e32 v102, 0xffff0000, v141
	v_fmac_f32_e32 v102, v103, v100
	v_lshlrev_b32_e32 v100, 16, v138
	v_lshlrev_b32_e32 v103, 16, v142
	v_fmac_f32_e32 v103, v92, v100
	v_and_b32_e32 v92, 0xffff0000, v138
	v_and_b32_e32 v100, 0xffff0000, v142
	v_fmac_f32_e32 v100, v93, v92
	v_lshlrev_b32_e32 v92, 16, v139
	v_lshlrev_b32_e32 v106, 16, v143
	v_fmac_f32_e32 v106, v94, v92
	v_and_b32_e32 v92, 0xffff0000, v139
	v_and_b32_e32 v107, 0xffff0000, v143
	v_fmac_f32_e32 v107, v95, v92
	v_cvt_pk_bf16_f32 v92, v105, v104
	v_cvt_pk_bf16_f32 v93, v101, v102
	v_cvt_pk_bf16_f32 v94, v103, v100
	v_cvt_pk_bf16_f32 v95, v106, v107
	global_store_dwordx4 v[214:215], v[92:95], off offset:256
	s_nop 1
	v_lshlrev_b32_e32 v92, 16, v144
	v_lshlrev_b32_e32 v93, 16, v148
	v_fmac_f32_e32 v93, v96, v92
	v_and_b32_e32 v92, 0xffff0000, v144
	v_and_b32_e32 v94, 0xffff0000, v148
	v_fmac_f32_e32 v94, v97, v92
	v_lshlrev_b32_e32 v92, 16, v145
	v_lshlrev_b32_e32 v95, 16, v149
	v_fmac_f32_e32 v95, v98, v92
	v_and_b32_e32 v92, 0xffff0000, v145
	v_and_b32_e32 v96, 0xffff0000, v149
	v_fmac_f32_e32 v96, v99, v92
	v_lshlrev_b32_e32 v92, 16, v146
	v_lshlrev_b32_e32 v97, 16, v150
	v_fmac_f32_e32 v97, v88, v92
	v_and_b32_e32 v88, 0xffff0000, v146
	v_and_b32_e32 v92, 0xffff0000, v150
	v_fmac_f32_e32 v92, v89, v88
	v_lshlrev_b32_e32 v88, 16, v147
	v_lshlrev_b32_e32 v98, 16, v151
	v_fmac_f32_e32 v98, v90, v88
	v_and_b32_e32 v88, 0xffff0000, v147
	v_and_b32_e32 v99, 0xffff0000, v151
	v_fmac_f32_e32 v99, v91, v88
	v_cvt_pk_bf16_f32 v88, v93, v94
	v_cvt_pk_bf16_f32 v89, v95, v96
	v_cvt_pk_bf16_f32 v90, v97, v92
	v_cvt_pk_bf16_f32 v91, v98, v99
	global_store_dwordx4 v[212:213], v[88:91], off
	s_nop 1
	v_lshlrev_b32_e32 v88, 16, v128
	v_lshlrev_b32_e32 v89, 16, v132
	v_fmac_f32_e32 v89, v84, v88
	v_and_b32_e32 v84, 0xffff0000, v128
	v_and_b32_e32 v88, 0xffff0000, v132
	v_fmac_f32_e32 v88, v85, v84
	v_lshlrev_b32_e32 v84, 16, v129
	v_lshlrev_b32_e32 v85, 16, v133
	v_fmac_f32_e32 v85, v86, v84
	v_and_b32_e32 v84, 0xffff0000, v129
	v_and_b32_e32 v86, 0xffff0000, v133
	v_fmac_f32_e32 v86, v87, v84
	v_lshlrev_b32_e32 v84, 16, v130
	v_lshlrev_b32_e32 v87, 16, v134
	v_fmac_f32_e32 v87, v76, v84
	v_and_b32_e32 v76, 0xffff0000, v130
	v_and_b32_e32 v84, 0xffff0000, v134
	v_fmac_f32_e32 v84, v77, v76
	v_lshlrev_b32_e32 v76, 16, v131
	v_lshlrev_b32_e32 v90, 16, v135
	v_fmac_f32_e32 v90, v78, v76
	v_and_b32_e32 v76, 0xffff0000, v131
	v_and_b32_e32 v91, 0xffff0000, v135
	v_fmac_f32_e32 v91, v79, v76
	v_cvt_pk_bf16_f32 v76, v89, v88
	v_cvt_pk_bf16_f32 v77, v85, v86
	v_cvt_pk_bf16_f32 v78, v87, v84
	v_cvt_pk_bf16_f32 v79, v90, v91
	global_store_dwordx4 v[212:213], v[76:79], off offset:256
	s_nop 1
	v_lshlrev_b32_e32 v76, 16, v168
	v_lshlrev_b32_e32 v77, 16, v172
	v_fmac_f32_e32 v77, v80, v76
	v_and_b32_e32 v76, 0xffff0000, v168
	v_and_b32_e32 v78, 0xffff0000, v172
	v_fmac_f32_e32 v78, v81, v76
	v_lshlrev_b32_e32 v76, 16, v169
	v_lshlrev_b32_e32 v79, 16, v173
	v_fmac_f32_e32 v79, v82, v76
	v_and_b32_e32 v76, 0xffff0000, v169
	v_and_b32_e32 v80, 0xffff0000, v173
	v_fmac_f32_e32 v80, v83, v76
	v_lshlrev_b32_e32 v76, 16, v170
	v_lshlrev_b32_e32 v81, 16, v174
	v_fmac_f32_e32 v81, v72, v76
	v_and_b32_e32 v72, 0xffff0000, v170
	v_and_b32_e32 v76, 0xffff0000, v174
	v_fmac_f32_e32 v76, v73, v72
	v_lshlrev_b32_e32 v72, 16, v171
	v_lshlrev_b32_e32 v82, 16, v175
	v_fmac_f32_e32 v82, v74, v72
	v_and_b32_e32 v72, 0xffff0000, v171
	v_and_b32_e32 v83, 0xffff0000, v175
	v_fmac_f32_e32 v83, v75, v72
	v_cvt_pk_bf16_f32 v72, v77, v78
	v_cvt_pk_bf16_f32 v73, v79, v80
	v_cvt_pk_bf16_f32 v74, v81, v76
	v_cvt_pk_bf16_f32 v75, v82, v83
	global_store_dwordx4 v[216:217], v[72:75], off
	s_nop 1
	v_lshlrev_b32_e32 v72, 16, v152
	v_lshlrev_b32_e32 v73, 16, v164
	v_fmac_f32_e32 v73, v68, v72
	v_and_b32_e32 v68, 0xffff0000, v152
; __device__ __forceinline__ unsigned cvt_pk_bf16(float lo, float hi) { unsigned r; asm volatile("v_cvt_pk_bf16_f32 %0, %1, %2" : "=v"(r) : "v"(lo), "v"(hi)); return r; }
; __device__ __forceinline__ float bflo(unsigned w) { return __uint_as_float(w << 16); }
; __device__ __forceinline__ float bfhi(unsigned w) { return __uint_as_float(w & 0xffff0000u); }
;     __device__ __forceinline__ void operator()(const f32x4 (&acc)[2][2][4][2], const Unit& u, int wr, int wc, int fr, int fq) const {
;     ...
;                 for (int bj = 0; bj < 2; ++bj) { const size_t r = (size_t)(row0 + ai * HALF + m * 16); const int c = col0 + bj * HALF;
;                     gv[m][bj] = *(const u32x4*)(Gt + r * N1 + c); ov[m][bj] = accum ? *(const u32x4*)(O + r * D + c) : (u32x4){0u, 0u, 0u, 0u}; }
; #pragma unroll
;             for (int m = 0; m < 4; ++m)
; #pragma unroll
;                 for (int bj = 0; bj < 2; ++bj) { const size_t r = (size_t)(row0 + ai * HALF + m * 16); const int c = col0 + bj * HALF;
;                     const u32x4 g = gv[m][bj], o0 = ov[m][bj];
;                     f32x4 v0 = acc[ai][bj][m][0], v1 = acc[ai][bj][m][1];
;                     v0[0] = v0[0] * bflo(g.x) + bflo(o0.x); v0[1] = v0[1] * bfhi(g.x) + bfhi(o0.x); v0[2] = v0[2] * bflo(g.y) + bflo(o0.y); v0[3] = v0[3] * bfhi(g.y) + bfhi(o0.y);
;                     v1[0] = v1[0] * bflo(g.z) + bflo(o0.z); v1[1] = v1[1] * bfhi(g.z) + bfhi(o0.z); v1[2] = v1[2] * bflo(g.w) + bflo(o0.w); v1[3] = v1[3] * bfhi(g.w) + bfhi(o0.w);
;                     u32x4 o; o.x = cvt_pk_bf16(v0[0], v0[1]); o.y = cvt_pk_bf16(v0[2], v0[3]); o.z = cvt_pk_bf16(v1[0], v1[1]); o.w = cvt_pk_bf16(v1[2], v1[3]);
;                     *(u32x4*)(O + r * D + c) = o; }
	v_and_b32_e32 v72, 0xffff0000, v164
	v_fmac_f32_e32 v72, v69, v68
	v_lshlrev_b32_e32 v68, 16, v153
	v_lshlrev_b32_e32 v69, 16, v165
	v_fmac_f32_e32 v69, v70, v68
	v_and_b32_e32 v68, 0xffff0000, v153
	v_and_b32_e32 v70, 0xffff0000, v165
	v_fmac_f32_e32 v70, v71, v68
	v_lshlrev_b32_e32 v68, 16, v154
	v_lshlrev_b32_e32 v71, 16, v166
	v_fmac_f32_e32 v71, v64, v68
	v_and_b32_e32 v64, 0xffff0000, v154
	v_and_b32_e32 v68, 0xffff0000, v166
	v_fmac_f32_e32 v68, v65, v64
	v_lshlrev_b32_e32 v64, 16, v155
	v_lshlrev_b32_e32 v74, 16, v167
	v_fmac_f32_e32 v74, v66, v64
	v_and_b32_e32 v64, 0xffff0000, v155
	v_and_b32_e32 v75, 0xffff0000, v167
	v_fmac_f32_e32 v75, v67, v64
	v_cvt_pk_bf16_f32 v64, v73, v72
	v_cvt_pk_bf16_f32 v65, v69, v70
	v_cvt_pk_bf16_f32 v66, v71, v68
	v_cvt_pk_bf16_f32 v67, v74, v75
	global_store_dwordx4 v[216:217], v[64:67], off offset:256
	s_nop 1
	v_add_u32_e32 v64, 0x80, v206
	v_ashrrev_i32_e32 v65, 31, v64
	v_mad_i64_i32 v[66:67], s[12:13], v64, s97, v[208:209]
	v_lshlrev_b64 v[64:65], 11, v[64:65]
	v_lshl_add_u64 v[66:67], v[66:67], 0, v[210:211]
	v_lshl_add_u64 v[64:65], s[24:25], 0, v[64:65]
	global_load_dwordx4 v[92:95], v[66:67], off
	v_lshl_add_u64 v[132:133], v[64:65], 0, v[210:211]
	global_load_dwordx4 v[96:99], v[132:133], off
	global_load_dwordx4 v[100:103], v[66:67], off offset:256
	global_load_dwordx4 v[104:107], v[132:133], off offset:256
	v_add_u32_e32 v64, 0x90, v206
	v_ashrrev_i32_e32 v65, 31, v64
	v_mad_i64_i32 v[66:67], s[12:13], v64, s97, v[208:209]
	v_lshlrev_b64 v[64:65], 11, v[64:65]
	v_lshl_add_u64 v[66:67], v[66:67], 0, v[210:211]
	v_lshl_add_u64 v[64:65], s[24:25], 0, v[64:65]
	global_load_dwordx4 v[108:111], v[66:67], off
	v_lshl_add_u64 v[134:135], v[64:65], 0, v[210:211]
	global_load_dwordx4 v[112:115], v[134:135], off
	global_load_dwordx4 v[116:119], v[66:67], off offset:256
	global_load_dwordx4 v[120:123], v[134:135], off offset:256
	v_add_u32_e32 v64, 0xa0, v206
	v_ashrrev_i32_e32 v65, 31, v64
	v_mad_i64_i32 v[66:67], s[12:13], v64, s97, v[208:209]
	v_lshlrev_b64 v[64:65], 11, v[64:65]
	v_lshl_add_u64 v[66:67], v[66:67], 0, v[210:211]
	v_lshl_add_u64 v[64:65], s[24:25], 0, v[64:65]
	global_load_dwordx4 v[124:127], v[66:67], off
	v_lshl_add_u64 v[90:91], v[64:65], 0, v[210:211]
	global_load_dwordx4 v[128:131], v[90:91], off
	global_load_dwordx4 v[80:83], v[66:67], off offset:256
	global_load_dwordx4 v[84:87], v[90:91], off offset:256
	v_add_u32_e32 v64, 0xb0, v206
	v_ashrrev_i32_e32 v65, 31, v64
	v_mad_i64_i32 v[66:67], s[12:13], v64, s97, v[208:209]
	v_lshlrev_b64 v[64:65], 11, v[64:65]
	v_lshl_add_u64 v[66:67], v[66:67], 0, v[210:211]
	v_lshl_add_u64 v[64:65], s[24:25], 0, v[64:65]
	global_load_dwordx4 v[72:75], v[66:67], off
	v_lshl_add_u64 v[88:89], v[64:65], 0, v[210:211]
	global_load_dwordx4 v[76:79], v[88:89], off
	s_nop 0
	global_load_dwordx4 v[64:67], v[66:67], off offset:256
	s_nop 0
	global_load_dwordx4 v[68:71], v[88:89], off offset:256
	s_mov_b64 s[12:13], -1
	s_waitcnt vmcnt(15)
	v_lshlrev_b32_e32 v136, 16, v92
	s_waitcnt vmcnt(14)
	v_lshlrev_b32_e32 v137, 16, v96
	v_fmac_f32_e32 v137, v60, v136
	v_and_b32_e32 v60, 0xffff0000, v92
	v_and_b32_e32 v92, 0xffff0000, v96
	v_fmac_f32_e32 v92, v61, v60
	v_lshlrev_b32_e32 v60, 16, v93
	v_lshlrev_b32_e32 v61, 16, v97
	v_fmac_f32_e32 v61, v62, v60
	v_and_b32_e32 v60, 0xffff0000, v93
	v_and_b32_e32 v62, 0xffff0000, v97
	v_fmac_f32_e32 v62, v63, v60
	v_lshlrev_b32_e32 v60, 16, v94
	v_lshlrev_b32_e32 v63, 16, v98
	v_fmac_f32_e32 v63, v56, v60
	v_and_b32_e32 v56, 0xffff0000, v94
	v_and_b32_e32 v60, 0xffff0000, v98
	v_fmac_f32_e32 v60, v57, v56
	v_lshlrev_b32_e32 v56, 16, v95
	v_lshlrev_b32_e32 v93, 16, v99
	v_fmac_f32_e32 v93, v58, v56
	v_and_b32_e32 v56, 0xffff0000, v95
	v_and_b32_e32 v94, 0xffff0000, v99
	v_fmac_f32_e32 v94, v59, v56
	v_cvt_pk_bf16_f32 v56, v137, v92
	v_cvt_pk_bf16_f32 v57, v61, v62
	v_cvt_pk_bf16_f32 v58, v63, v60
	v_cvt_pk_bf16_f32 v59, v93, v94
	global_store_dwordx4 v[132:133], v[56:59], off
	s_waitcnt vmcnt(14)
	s_nop 0
	v_lshlrev_b32_e32 v56, 16, v100
	s_waitcnt vmcnt(13)
	v_lshlrev_b32_e32 v57, 16, v104
	v_fmac_f32_e32 v57, v52, v56
	v_and_b32_e32 v52, 0xffff0000, v100
	v_and_b32_e32 v56, 0xffff0000, v104
	v_fmac_f32_e32 v56, v53, v52
	v_lshlrev_b32_e32 v52, 16, v101
	v_lshlrev_b32_e32 v53, 16, v105
	v_fmac_f32_e32 v53, v54, v52
	v_and_b32_e32 v52, 0xffff0000, v101
	v_and_b32_e32 v54, 0xffff0000, v105
	v_fmac_f32_e32 v54, v55, v52
	v_lshlrev_b32_e32 v52, 16, v102
	v_lshlrev_b32_e32 v55, 16, v106
	v_fmac_f32_e32 v55, v44, v52
	v_and_b32_e32 v44, 0xffff0000, v102
	v_and_b32_e32 v52, 0xffff0000, v106
	v_fmac_f32_e32 v52, v45, v44
	v_lshlrev_b32_e32 v44, 16, v103
	v_lshlrev_b32_e32 v58, 16, v107
	v_fmac_f32_e32 v58, v46, v44
	v_and_b32_e32 v44, 0xffff0000, v103
	v_and_b32_e32 v59, 0xffff0000, v107
	v_fmac_f32_e32 v59, v47, v44
	v_cvt_pk_bf16_f32 v44, v57, v56
	v_cvt_pk_bf16_f32 v45, v53, v54
	v_cvt_pk_bf16_f32 v46, v55, v52
	v_cvt_pk_bf16_f32 v47, v58, v59
	global_store_dwordx4 v[132:133], v[44:47], off offset:256
	s_waitcnt vmcnt(13)
	s_nop 0
	v_lshlrev_b32_e32 v44, 16, v108
	s_waitcnt vmcnt(12)
	v_lshlrev_b32_e32 v45, 16, v112
	v_fmac_f32_e32 v45, v48, v44
	v_and_b32_e32 v44, 0xffff0000, v108
	v_and_b32_e32 v46, 0xffff0000, v112
	v_fmac_f32_e32 v46, v49, v44
	v_lshlrev_b32_e32 v44, 16, v109
	v_lshlrev_b32_e32 v47, 16, v113
	v_fmac_f32_e32 v47, v50, v44
	v_and_b32_e32 v44, 0xffff0000, v109
	v_and_b32_e32 v48, 0xffff0000, v113
	v_fmac_f32_e32 v48, v51, v44
	v_lshlrev_b32_e32 v44, 16, v110
	v_lshlrev_b32_e32 v49, 16, v114
	v_fmac_f32_e32 v49, v40, v44
	v_and_b32_e32 v40, 0xffff0000, v110
	v_and_b32_e32 v44, 0xffff0000, v114
	v_fmac_f32_e32 v44, v41, v40
	v_lshlrev_b32_e32 v40, 16, v111
	v_lshlrev_b32_e32 v50, 16, v115
	v_fmac_f32_e32 v50, v42, v40
	v_and_b32_e32 v40, 0xffff0000, v111
	v_and_b32_e32 v51, 0xffff0000, v115
	v_fmac_f32_e32 v51, v43, v40
	v_cvt_pk_bf16_f32 v40, v45, v46
	v_cvt_pk_bf16_f32 v41, v47, v48
	v_cvt_pk_bf16_f32 v42, v49, v44
	v_cvt_pk_bf16_f32 v43, v50, v51
	global_store_dwordx4 v[134:135], v[40:43], off
	s_waitcnt vmcnt(12)
; __device__ __forceinline__ unsigned cvt_pk_bf16(float lo, float hi) { unsigned r; asm volatile("v_cvt_pk_bf16_f32 %0, %1, %2" : "=v"(r) : "v"(lo), "v"(hi)); return r; }
; __device__ __forceinline__ float bflo(unsigned w) { return __uint_as_float(w << 16); }
; __device__ __forceinline__ float bfhi(unsigned w) { return __uint_as_float(w & 0xffff0000u); }
;     __device__ __forceinline__ void operator()(const f32x4 (&acc)[2][2][4][2], const Unit& u, int wr, int wc, int fr, int fq) const {
;     ...
;             for (int m = 0; m < 4; ++m)
; #pragma unroll
;                 for (int bj = 0; bj < 2; ++bj) { const size_t r = (size_t)(row0 + ai * HALF + m * 16); const int c = col0 + bj * HALF;
;                     const u32x4 g = gv[m][bj], o0 = ov[m][bj];
;                     f32x4 v0 = acc[ai][bj][m][0], v1 = acc[ai][bj][m][1];
;                     v0[0] = v0[0] * bflo(g.x) + bflo(o0.x); v0[1] = v0[1] * bfhi(g.x) + bfhi(o0.x); v0[2] = v0[2] * bflo(g.y) + bflo(o0.y); v0[3] = v0[3] * bfhi(g.y) + bfhi(o0.y);
;                     v1[0] = v1[0] * bflo(g.z) + bflo(o0.z); v1[1] = v1[1] * bfhi(g.z) + bfhi(o0.z); v1[2] = v1[2] * bflo(g.w) + bflo(o0.w); v1[3] = v1[3] * bfhi(g.w) + bfhi(o0.w);
;                     u32x4 o; o.x = cvt_pk_bf16(v0[0], v0[1]); o.y = cvt_pk_bf16(v0[2], v0[3]); o.z = cvt_pk_bf16(v1[0], v1[1]); o.w = cvt_pk_bf16(v1[2], v1[3]);
;                     *(u32x4*)(O + r * D + c) = o; }
	s_nop 0
	v_lshlrev_b32_e32 v40, 16, v116
	s_waitcnt vmcnt(11)
	v_lshlrev_b32_e32 v41, 16, v120
	v_fmac_f32_e32 v41, v36, v40
	v_and_b32_e32 v36, 0xffff0000, v116
	v_and_b32_e32 v40, 0xffff0000, v120
	v_fmac_f32_e32 v40, v37, v36
	v_lshlrev_b32_e32 v36, 16, v117
	v_lshlrev_b32_e32 v37, 16, v121
	v_fmac_f32_e32 v37, v38, v36
	v_and_b32_e32 v36, 0xffff0000, v117
	v_and_b32_e32 v38, 0xffff0000, v121
	v_fmac_f32_e32 v38, v39, v36
	v_lshlrev_b32_e32 v36, 16, v118
	v_lshlrev_b32_e32 v39, 16, v122
	v_fmac_f32_e32 v39, v28, v36
	v_and_b32_e32 v28, 0xffff0000, v118
	v_and_b32_e32 v36, 0xffff0000, v122
	v_fmac_f32_e32 v36, v29, v28
	v_lshlrev_b32_e32 v28, 16, v119
	v_lshlrev_b32_e32 v42, 16, v123
	v_fmac_f32_e32 v42, v30, v28
	v_and_b32_e32 v28, 0xffff0000, v119
	v_and_b32_e32 v43, 0xffff0000, v123
	v_fmac_f32_e32 v43, v31, v28
	v_cvt_pk_bf16_f32 v28, v41, v40
	v_cvt_pk_bf16_f32 v29, v37, v38
	v_cvt_pk_bf16_f32 v30, v39, v36
	v_cvt_pk_bf16_f32 v31, v42, v43
	global_store_dwordx4 v[134:135], v[28:31], off offset:256
	s_waitcnt vmcnt(11)
	s_nop 0
	v_lshlrev_b32_e32 v28, 16, v124
	s_waitcnt vmcnt(10)
	v_lshlrev_b32_e32 v29, 16, v128
	v_fmac_f32_e32 v29, v32, v28
	v_and_b32_e32 v28, 0xffff0000, v124
	v_and_b32_e32 v30, 0xffff0000, v128
	v_fmac_f32_e32 v30, v33, v28
	v_lshlrev_b32_e32 v28, 16, v125
	v_lshlrev_b32_e32 v31, 16, v129
	v_fmac_f32_e32 v31, v34, v28
	v_and_b32_e32 v28, 0xffff0000, v125
	v_and_b32_e32 v32, 0xffff0000, v129
	v_fmac_f32_e32 v32, v35, v28
	v_lshlrev_b32_e32 v28, 16, v126
	v_lshlrev_b32_e32 v33, 16, v130
	v_fmac_f32_e32 v33, v24, v28
	v_and_b32_e32 v24, 0xffff0000, v126
	v_and_b32_e32 v28, 0xffff0000, v130
	v_fmac_f32_e32 v28, v25, v24
	v_lshlrev_b32_e32 v24, 16, v127
	v_lshlrev_b32_e32 v34, 16, v131
	v_fmac_f32_e32 v34, v26, v24
	v_and_b32_e32 v24, 0xffff0000, v127
	v_and_b32_e32 v35, 0xffff0000, v131
	v_fmac_f32_e32 v35, v27, v24
	v_cvt_pk_bf16_f32 v24, v29, v30
	v_cvt_pk_bf16_f32 v25, v31, v32
	v_cvt_pk_bf16_f32 v26, v33, v28
	v_cvt_pk_bf16_f32 v27, v34, v35
	global_store_dwordx4 v[90:91], v[24:27], off
	s_waitcnt vmcnt(10)
	s_nop 0
	v_lshlrev_b32_e32 v24, 16, v80
	s_waitcnt vmcnt(9)
	v_lshlrev_b32_e32 v25, 16, v84
	v_fmac_f32_e32 v25, v20, v24
	v_and_b32_e32 v20, 0xffff0000, v80
	v_and_b32_e32 v24, 0xffff0000, v84
	v_fmac_f32_e32 v24, v21, v20
	v_lshlrev_b32_e32 v20, 16, v81
	v_lshlrev_b32_e32 v21, 16, v85
	v_fmac_f32_e32 v21, v22, v20
	v_and_b32_e32 v20, 0xffff0000, v81
	v_and_b32_e32 v22, 0xffff0000, v85
	v_fmac_f32_e32 v22, v23, v20
	v_lshlrev_b32_e32 v20, 16, v82
	v_lshlrev_b32_e32 v23, 16, v86
	v_fmac_f32_e32 v23, v12, v20
	v_and_b32_e32 v12, 0xffff0000, v82
	v_and_b32_e32 v20, 0xffff0000, v86
	v_fmac_f32_e32 v20, v13, v12
	v_lshlrev_b32_e32 v12, 16, v83
	v_lshlrev_b32_e32 v26, 16, v87
	v_fmac_f32_e32 v26, v14, v12
	v_and_b32_e32 v12, 0xffff0000, v83
	v_and_b32_e32 v27, 0xffff0000, v87
	v_fmac_f32_e32 v27, v15, v12
	v_cvt_pk_bf16_f32 v12, v25, v24
	v_cvt_pk_bf16_f32 v13, v21, v22
	v_cvt_pk_bf16_f32 v14, v23, v20
	v_cvt_pk_bf16_f32 v15, v26, v27
	global_store_dwordx4 v[90:91], v[12:15], off offset:256
	s_waitcnt vmcnt(9)
	s_nop 0
	v_lshlrev_b32_e32 v12, 16, v72
	s_waitcnt vmcnt(8)
	v_lshlrev_b32_e32 v13, 16, v76
	v_fmac_f32_e32 v13, v16, v12
	v_and_b32_e32 v12, 0xffff0000, v72
	v_and_b32_e32 v14, 0xffff0000, v76
	v_fmac_f32_e32 v14, v17, v12
	v_lshlrev_b32_e32 v12, 16, v73
	v_lshlrev_b32_e32 v15, 16, v77
	v_fmac_f32_e32 v15, v18, v12
	v_and_b32_e32 v12, 0xffff0000, v73
	v_and_b32_e32 v16, 0xffff0000, v77
	v_fmac_f32_e32 v16, v19, v12
	v_lshlrev_b32_e32 v12, 16, v74
	v_lshlrev_b32_e32 v17, 16, v78
	v_fmac_f32_e32 v17, v8, v12
	v_and_b32_e32 v8, 0xffff0000, v74
	v_and_b32_e32 v12, 0xffff0000, v78
	v_fmac_f32_e32 v12, v9, v8
	v_lshlrev_b32_e32 v8, 16, v75
	v_lshlrev_b32_e32 v18, 16, v79
	v_fmac_f32_e32 v18, v10, v8
	v_and_b32_e32 v8, 0xffff0000, v75
	v_and_b32_e32 v19, 0xffff0000, v79
	v_fmac_f32_e32 v19, v11, v8
	v_cvt_pk_bf16_f32 v8, v13, v14
	v_cvt_pk_bf16_f32 v9, v15, v16
	v_cvt_pk_bf16_f32 v10, v17, v12
	v_cvt_pk_bf16_f32 v11, v18, v19
	global_store_dwordx4 v[88:89], v[8:11], off
	s_waitcnt vmcnt(8)
	s_nop 0
	v_lshlrev_b32_e32 v8, 16, v64
	s_waitcnt vmcnt(7)
	v_lshlrev_b32_e32 v9, 16, v68
	v_fmac_f32_e32 v9, v4, v8
	v_and_b32_e32 v4, 0xffff0000, v64
	v_and_b32_e32 v8, 0xffff0000, v68
	v_fmac_f32_e32 v8, v5, v4
	v_lshlrev_b32_e32 v4, 16, v65
	v_lshlrev_b32_e32 v5, 16, v69
	v_fmac_f32_e32 v5, v6, v4
	v_and_b32_e32 v4, 0xffff0000, v65
	v_and_b32_e32 v6, 0xffff0000, v69
	v_fmac_f32_e32 v6, v7, v4
	v_lshlrev_b32_e32 v4, 16, v66
	v_lshlrev_b32_e32 v7, 16, v70
	v_fmac_f32_e32 v7, v0, v4
	v_and_b32_e32 v0, 0xffff0000, v66
	v_and_b32_e32 v4, 0xffff0000, v70
	v_fmac_f32_e32 v4, v1, v0
	v_lshlrev_b32_e32 v0, 16, v67
	v_lshlrev_b32_e32 v10, 16, v71
	v_fmac_f32_e32 v10, v2, v0
	v_and_b32_e32 v0, 0xffff0000, v67
	v_and_b32_e32 v11, 0xffff0000, v71
	v_fmac_f32_e32 v11, v3, v0
	v_cvt_pk_bf16_f32 v0, v9, v8
	v_cvt_pk_bf16_f32 v1, v5, v6
	v_cvt_pk_bf16_f32 v2, v7, v4
	v_cvt_pk_bf16_f32 v3, v10, v11
	global_store_dwordx4 v[88:89], v[0:3], off offset:256
	s_cbranch_vccnz .LBB0_429
	s_andn2_b64 vcc, exec, s[0:1]
	s_cbranch_vccnz .LBB0_428
	s_barrier
	s_branch .LBB0_428

; #define LAS __attribute__((address_space(3)))
;     __device__ __forceinline__ void operator()(const f32x4 (&acc)[2][2][4][2], const Unit& u, int wr, int wc, int fr, int fq) const {
;     ...
;         if (fr >= 14) {
; #pragma unroll
;             for (int ai = 0; ai < 2; ++ai) { LAS float* hp = halo + ((ai * 2 + wr) * 2 + (fr - 14)) * 128 + wc * 32 + 8 * fq; *(LAS f32x4*)hp = acc[ai][0][3][0]; *(LAS f32x4*)(hp + 4) = acc[ai][0][3][1]; }
;         }
;         asm volatile("s_waitcnt lgkmcnt(0)" ::: "memory"); __builtin_amdgcn_s_barrier(); asm volatile("" ::: "memory");
;         const int lane = fq * 16 + fr, src1 = (lane & 48) | ((fr + 15) & 15), src2 = (lane & 48) | ((fr + 14) & 15);
.LBB0_671:
	s_mov_b32 s98, 0xbfb8aa3b
	s_and_saveexec_b64 s[0:1], s[40:41]
	s_cbranch_execz .LBB0_673
	ds_write_b128 v181, v[108:111]
	ds_write_b128 v181, v[32:35] offset:16
	ds_write_b128 v180, v[64:67]
	ds_write_b128 v180, v[4:7] offset:16

; __device__ __forceinline__ unsigned cvt_pk_bf16(float lo, float hi) { unsigned r; asm volatile("v_cvt_pk_bf16_f32 %0, %1, %2" : "=v"(r) : "v"(lo), "v"(hi)); return r; }
; __device__ __forceinline__ float fsigmoid(float x) { return __builtin_amdgcn_rcpf(1.f + __expf(-x)); }
;     __device__ __forceinline__ void operator()(const f32x4 (&acc)[2][2][4][2], const Unit& u, int wr, int wc, int fr, int fq) const {
;     ...
;                     if (valid) {
;                         const f32x4 v4 = acc[ai][1][m][n];
;                         float o[4];
; #pragma unroll
;                         for (int e = 0; e < 4; ++e) { const float y = w0[e] * p2[e] + w1[e] * p1[e] + w2[e] * g4[e]; o[e] = y * fsigmoid(y) * v4[e]; }
;                         u32x2 ov; ov.x = cvt_pk_bf16(o[0], o[1]); ov.y = cvt_pk_bf16(o[2], o[3]);
;                         *(u32x2*)(ACT + (size_t)Rl * DFF + col) = ov;
;                         if (t >= Lq - 2) *(f32x4*)((smp ? stout_s : stout_p) + (size_t)((l * 16 + sq) * 2 + (t - (Lq - 2))) * DFF + col) = g4;
.LBB0_685:
	s_or_b64 exec, exec, s[0:1]
	s_waitcnt vmcnt(0)
	s_and_saveexec_b64 s[0:1], s[10:11]
	s_cbranch_execz .LBB0_688
	s_waitcnt lgkmcnt(0)
	v_cmp_ge_u32_e32 vcc, v196, v199
	v_pk_mul_f32 v[144:145], v[88:89], v[144:145]
	v_pk_mul_f32 v[146:147], v[90:91], v[146:147]
	v_pk_fma_f32 v[144:145], v[92:93], v[140:141], v[144:145]
	v_pk_fma_f32 v[146:147], v[94:95], v[142:143], v[146:147]
	v_pk_fma_f32 v[144:145], v[96:97], v[132:133], v[144:145]
	v_pk_fma_f32 v[146:147], v[98:99], v[134:135], v[146:147]
	v_pk_mul_f32 v[140:141], v[144:145], s[98:99] op_sel_hi:[1,0]
	v_pk_mul_f32 v[142:143], v[146:147], s[98:99] op_sel_hi:[1,0]
	v_exp_f32_e32 v140, v140
	v_exp_f32_e32 v141, v141
	v_exp_f32_e32 v142, v142
	v_exp_f32_e32 v143, v143
	v_pk_add_f32 v[140:141], v[140:141], 1.0 op_sel_hi:[1,0]
	v_pk_add_f32 v[142:143], v[142:143], 1.0 op_sel_hi:[1,0]
	v_rcp_f32_e32 v140, v140
	v_rcp_f32_e32 v141, v141
	v_rcp_f32_e32 v142, v142
	v_rcp_f32_e32 v143, v143
	v_pk_mul_f32 v[144:145], v[144:145], v[140:141]
	v_pk_mul_f32 v[146:147], v[146:147], v[142:143]
	v_pk_mul_f32 v[136:137], v[136:137], v[144:145]
	v_pk_mul_f32 v[138:139], v[138:139], v[146:147]
	v_cvt_pk_bf16_f32 v136, v136, v137
	v_cvt_pk_bf16_f32 v137, v138, v139
	v_mov_b64_e32 v[138:139], s[56:57]
	v_mad_i64_i32 v[138:139], s[2:3], v190, s59, v[138:139]
	v_lshl_add_u64 v[138:139], v[172:173], 1, v[138:139]
	global_store_dwordx2 v[138:139], v[136:137], off
	s_and_b64 exec, exec, vcc
	s_cbranch_execz .LBB0_688
	v_readlane_b32 s2, v249, 51
	v_sub_u32_e32 v139, s96, v199
	s_nop 0
	v_mov_b32_e32 v136, s2
	v_readlane_b32 s2, v249, 53
	s_nop 1
	v_mov_b32_e32 v137, s2
	v_readlane_b32 s2, v249, 50
	v_cndmask_b32_e64 v137, v136, v137, s[44:45]
	s_nop 0
	v_mov_b32_e32 v136, s2
	v_readlane_b32 s2, v249, 52
	s_nop 1
	v_mov_b32_e32 v138, s2
	v_cndmask_b32_e64 v136, v136, v138, s[44:45]
	v_lshlrev_b32_e32 v138, 1, v198
	v_add3_u32 v138, v139, v138, v196
	v_mad_i64_i32 v[136:137], s[2:3], v138, s97, v[136:137]
	v_lshl_add_u64 v[136:137], v[172:173], 2, v[136:137]
	global_store_dwordx4 v[136:137], v[132:135], off

; __device__ __forceinline__ unsigned cvt_pk_bf16(float lo, float hi) { unsigned r; asm volatile("v_cvt_pk_bf16_f32 %0, %1, %2" : "=v"(r) : "v"(lo), "v"(hi)); return r; }
; __device__ __forceinline__ float fsigmoid(float x) { return __builtin_amdgcn_rcpf(1.f + __expf(-x)); }
;     __device__ __forceinline__ void operator()(const f32x4 (&acc)[2][2][4][2], const Unit& u, int wr, int wc, int fr, int fq) const {
;     ...
;                     if (valid) {
;                         const f32x4 v4 = acc[ai][1][m][n];
;                         float o[4];
; #pragma unroll
;                         for (int e = 0; e < 4; ++e) { const float y = w0[e] * p2[e] + w1[e] * p1[e] + w2[e] * g4[e]; o[e] = y * fsigmoid(y) * v4[e]; }
;                         u32x2 ov; ov.x = cvt_pk_bf16(o[0], o[1]); ov.y = cvt_pk_bf16(o[2], o[3]);
;                         *(u32x2*)(ACT + (size_t)Rl * DFF + col) = ov;
;                         if (t >= Lq - 2) *(f32x4*)((smp ? stout_s : stout_p) + (size_t)((l * 16 + sq) * 2 + (t - (Lq - 2))) * DFF + col) = g4;
.LBB0_696:
	s_or_b64 exec, exec, s[2:3]
	s_and_saveexec_b64 s[2:3], s[0:1]
	s_cbranch_execz .LBB0_699
	v_cmp_ge_u32_e32 vcc, v198, v200
	v_pk_mul_f32 v[138:139], v[88:89], v[138:139]
	v_pk_mul_f32 v[134:135], v[90:91], v[134:135]
	v_pk_fma_f32 v[138:139], v[92:93], v[136:137], v[138:139]
	v_pk_fma_f32 v[134:135], v[94:95], v[132:133], v[134:135]
	v_pk_fma_f32 v[138:139], v[96:97], v[124:125], v[138:139]
	v_pk_fma_f32 v[134:135], v[98:99], v[126:127], v[134:135]
	v_pk_mul_f32 v[136:137], v[138:139], s[98:99] op_sel_hi:[1,0]
	v_pk_mul_f32 v[132:133], v[134:135], s[98:99] op_sel_hi:[1,0]
	v_exp_f32_e32 v136, v136
	v_exp_f32_e32 v137, v137
	v_exp_f32_e32 v132, v132
	v_exp_f32_e32 v133, v133
	v_pk_add_f32 v[136:137], v[136:137], 1.0 op_sel_hi:[1,0]
	v_pk_add_f32 v[132:133], v[132:133], 1.0 op_sel_hi:[1,0]
	v_rcp_f32_e32 v136, v136
	v_rcp_f32_e32 v137, v137
	v_rcp_f32_e32 v132, v132
	v_rcp_f32_e32 v133, v133
	v_pk_mul_f32 v[138:139], v[138:139], v[136:137]
	v_pk_mul_f32 v[134:135], v[134:135], v[132:133]
	v_pk_mul_f32 v[128:129], v[128:129], v[138:139]
	v_pk_mul_f32 v[130:131], v[130:131], v[134:135]
	v_cvt_pk_bf16_f32 v128, v128, v129
	v_cvt_pk_bf16_f32 v129, v130, v131
	v_mov_b64_e32 v[130:131], s[56:57]
	v_mad_i64_i32 v[130:131], s[8:9], v150, s59, v[130:131]
	v_lshl_add_u64 v[130:131], v[172:173], 1, v[130:131]
	global_store_dwordx2 v[130:131], v[128:129], off
	s_and_b64 exec, exec, vcc
	s_cbranch_execz .LBB0_699
	v_readlane_b32 s8, v249, 51
	v_sub_u32_e32 v131, s96, v200
	s_nop 0
	v_mov_b32_e32 v128, s8
	v_readlane_b32 s8, v249, 53
	s_nop 1
	v_mov_b32_e32 v129, s8
	v_readlane_b32 s8, v249, 50
	v_cndmask_b32_e64 v129, v128, v129, s[16:17]
	s_nop 0
	v_mov_b32_e32 v128, s8
	v_readlane_b32 s8, v249, 52
	s_nop 1
	v_mov_b32_e32 v130, s8
	v_cndmask_b32_e64 v128, v128, v130, s[16:17]
	v_lshlrev_b32_e32 v130, 1, v199
	v_add3_u32 v130, v131, v130, v198
	v_mad_i64_i32 v[128:129], s[8:9], v130, s97, v[128:129]
	v_lshl_add_u64 v[128:129], v[172:173], 2, v[128:129]
	global_store_dwordx4 v[128:129], v[124:127], off

; __device__ __forceinline__ unsigned cvt_pk_bf16(float lo, float hi) { unsigned r; asm volatile("v_cvt_pk_bf16_f32 %0, %1, %2" : "=v"(r) : "v"(lo), "v"(hi)); return r; }
; __device__ __forceinline__ float fsigmoid(float x) { return __builtin_amdgcn_rcpf(1.f + __expf(-x)); }
;     __device__ __forceinline__ void operator()(const f32x4 (&acc)[2][2][4][2], const Unit& u, int wr, int wc, int fr, int fq) const {
;     ...
;                     if (valid) {
;                         const f32x4 v4 = acc[ai][1][m][n];
;                         float o[4];
; #pragma unroll
;                         for (int e = 0; e < 4; ++e) { const float y = w0[e] * p2[e] + w1[e] * p1[e] + w2[e] * g4[e]; o[e] = y * fsigmoid(y) * v4[e]; }
;                         u32x2 ov; ov.x = cvt_pk_bf16(o[0], o[1]); ov.y = cvt_pk_bf16(o[2], o[3]);
;                         *(u32x2*)(ACT + (size_t)Rl * DFF + col) = ov;
;                         if (t >= Lq - 2) *(f32x4*)((smp ? stout_s : stout_p) + (size_t)((l * 16 + sq) * 2 + (t - (Lq - 2))) * DFF + col) = g4;
.LBB0_707:
	s_or_b64 exec, exec, s[2:3]
	s_and_saveexec_b64 s[2:3], s[8:9]
	s_cbranch_execz .LBB0_710
	v_cmp_ge_u32_e32 vcc, v145, v147
	v_pk_mul_f32 v[130:131], v[88:89], v[130:131]
	v_pk_mul_f32 v[126:127], v[90:91], v[126:127]
	v_pk_fma_f32 v[130:131], v[92:93], v[128:129], v[130:131]
	v_pk_fma_f32 v[126:127], v[94:95], v[124:125], v[126:127]
	v_pk_fma_f32 v[130:131], v[96:97], v[116:117], v[130:131]
	v_pk_fma_f32 v[126:127], v[98:99], v[118:119], v[126:127]
	v_pk_mul_f32 v[128:129], v[130:131], s[98:99] op_sel_hi:[1,0]
	v_pk_mul_f32 v[124:125], v[126:127], s[98:99] op_sel_hi:[1,0]
	v_exp_f32_e32 v128, v128
	v_exp_f32_e32 v129, v129
	v_exp_f32_e32 v124, v124
	v_exp_f32_e32 v125, v125
	v_pk_add_f32 v[128:129], v[128:129], 1.0 op_sel_hi:[1,0]
	v_pk_add_f32 v[124:125], v[124:125], 1.0 op_sel_hi:[1,0]
	v_rcp_f32_e32 v128, v128
	v_rcp_f32_e32 v129, v129
	v_rcp_f32_e32 v124, v124
	v_rcp_f32_e32 v125, v125
	v_pk_mul_f32 v[130:131], v[130:131], v[128:129]
	v_pk_mul_f32 v[126:127], v[126:127], v[124:125]
	v_pk_mul_f32 v[120:121], v[120:121], v[130:131]
	v_pk_mul_f32 v[122:123], v[122:123], v[126:127]
	v_cvt_pk_bf16_f32 v120, v120, v121
	v_cvt_pk_bf16_f32 v121, v122, v123
	v_mov_b64_e32 v[122:123], s[56:57]
	v_mad_i64_i32 v[122:123], s[12:13], v142, s59, v[122:123]
	v_lshl_add_u64 v[122:123], v[172:173], 1, v[122:123]
	global_store_dwordx2 v[122:123], v[120:121], off
	s_and_b64 exec, exec, vcc
	s_cbranch_execz .LBB0_710
	v_readlane_b32 s12, v249, 51
	v_sub_u32_e32 v123, s96, v147
	s_nop 0
	v_mov_b32_e32 v120, s12
	v_readlane_b32 s12, v249, 53
	s_nop 1
	v_mov_b32_e32 v121, s12
	v_readlane_b32 s12, v249, 50
	v_cndmask_b32_e64 v121, v120, v121, s[18:19]
	s_nop 0
	v_mov_b32_e32 v120, s12
	v_readlane_b32 s12, v249, 52
	s_nop 1
	v_mov_b32_e32 v122, s12
	v_cndmask_b32_e64 v120, v120, v122, s[18:19]
	v_lshlrev_b32_e32 v122, 1, v146
	v_add3_u32 v122, v123, v122, v145
	v_mad_i64_i32 v[120:121], s[12:13], v122, s97, v[120:121]
	v_lshl_add_u64 v[120:121], v[172:173], 2, v[120:121]
	global_store_dwordx4 v[120:121], v[116:119], off

; __device__ __forceinline__ unsigned cvt_pk_bf16(float lo, float hi) { unsigned r; asm volatile("v_cvt_pk_bf16_f32 %0, %1, %2" : "=v"(r) : "v"(lo), "v"(hi)); return r; }
; __device__ __forceinline__ float fsigmoid(float x) { return __builtin_amdgcn_rcpf(1.f + __expf(-x)); }
;     __device__ __forceinline__ void operator()(const f32x4 (&acc)[2][2][4][2], const Unit& u, int wr, int wc, int fr, int fq) const {
;     ...
;                     if (valid) {
;                         const f32x4 v4 = acc[ai][1][m][n];
;                         float o[4];
; #pragma unroll
;                         for (int e = 0; e < 4; ++e) { const float y = w0[e] * p2[e] + w1[e] * p1[e] + w2[e] * g4[e]; o[e] = y * fsigmoid(y) * v4[e]; }
;                         u32x2 ov; ov.x = cvt_pk_bf16(o[0], o[1]); ov.y = cvt_pk_bf16(o[2], o[3]);
;                         *(u32x2*)(ACT + (size_t)Rl * DFF + col) = ov;
;                         if (t >= Lq - 2) *(f32x4*)((smp ? stout_s : stout_p) + (size_t)((l * 16 + sq) * 2 + (t - (Lq - 2))) * DFF + col) = g4;
.LBB0_718:
	s_or_b64 exec, exec, s[2:3]
	s_and_saveexec_b64 s[2:3], s[12:13]
	s_cbranch_execz .LBB0_721
	v_cmp_ge_u32_e32 vcc, v137, v139
	v_pk_mul_f32 v[122:123], v[88:89], v[122:123]
	v_pk_mul_f32 v[118:119], v[90:91], v[118:119]
	v_pk_fma_f32 v[122:123], v[92:93], v[120:121], v[122:123]
	v_pk_fma_f32 v[118:119], v[94:95], v[116:117], v[118:119]
	v_pk_fma_f32 v[122:123], v[96:97], v[108:109], v[122:123]
	v_pk_fma_f32 v[118:119], v[98:99], v[110:111], v[118:119]
	v_pk_mul_f32 v[120:121], v[122:123], s[98:99] op_sel_hi:[1,0]
	v_pk_mul_f32 v[116:117], v[118:119], s[98:99] op_sel_hi:[1,0]
	v_exp_f32_e32 v120, v120
	v_exp_f32_e32 v121, v121
	v_exp_f32_e32 v116, v116
	v_exp_f32_e32 v117, v117
	v_pk_add_f32 v[120:121], v[120:121], 1.0 op_sel_hi:[1,0]
	v_pk_add_f32 v[116:117], v[116:117], 1.0 op_sel_hi:[1,0]
	v_rcp_f32_e32 v120, v120
	v_rcp_f32_e32 v121, v121
	v_rcp_f32_e32 v116, v116
	v_rcp_f32_e32 v117, v117
	v_pk_mul_f32 v[122:123], v[122:123], v[120:121]
	v_pk_mul_f32 v[118:119], v[118:119], v[116:117]
	v_pk_mul_f32 v[112:113], v[112:113], v[122:123]
	v_pk_mul_f32 v[114:115], v[114:115], v[118:119]
	v_cvt_pk_bf16_f32 v112, v112, v113
	v_cvt_pk_bf16_f32 v113, v114, v115
	v_mov_b64_e32 v[114:115], s[56:57]
	v_mad_i64_i32 v[114:115], s[46:47], v134, s59, v[114:115]
	v_lshl_add_u64 v[114:115], v[172:173], 1, v[114:115]
	global_store_dwordx2 v[114:115], v[112:113], off
	s_and_b64 exec, exec, vcc
	s_cbranch_execz .LBB0_721
	v_readlane_b32 s21, v249, 51
	v_sub_u32_e32 v115, s96, v139
	s_nop 0
	v_mov_b32_e32 v112, s21
	v_readlane_b32 s21, v249, 53
	s_nop 1
	v_mov_b32_e32 v113, s21
	v_readlane_b32 s21, v249, 50
	v_cndmask_b32_e64 v113, v112, v113, s[92:93]
	s_nop 0
	v_mov_b32_e32 v112, s21
	v_readlane_b32 s21, v249, 52
	s_nop 1
	v_mov_b32_e32 v114, s21
	v_cndmask_b32_e64 v112, v112, v114, s[92:93]
	v_lshlrev_b32_e32 v114, 1, v138
	v_add3_u32 v114, v115, v114, v137
	v_mad_i64_i32 v[112:113], s[46:47], v114, s97, v[112:113]
	v_lshl_add_u64 v[112:113], v[172:173], 2, v[112:113]
	global_store_dwordx4 v[112:113], v[108:111], off

; __device__ __forceinline__ unsigned cvt_pk_bf16(float lo, float hi) { unsigned r; asm volatile("v_cvt_pk_bf16_f32 %0, %1, %2" : "=v"(r) : "v"(lo), "v"(hi)); return r; }
; __device__ __forceinline__ float fsigmoid(float x) { return __builtin_amdgcn_rcpf(1.f + __expf(-x)); }
;     __device__ __forceinline__ void operator()(const f32x4 (&acc)[2][2][4][2], const Unit& u, int wr, int wc, int fr, int fq) const {
;     ...
;                     if (valid) {
;                         const f32x4 v4 = acc[ai][1][m][n];
;                         float o[4];
; #pragma unroll
;                         for (int e = 0; e < 4; ++e) { const float y = w0[e] * p2[e] + w1[e] * p1[e] + w2[e] * g4[e]; o[e] = y * fsigmoid(y) * v4[e]; }
;                         u32x2 ov; ov.x = cvt_pk_bf16(o[0], o[1]); ov.y = cvt_pk_bf16(o[2], o[3]);
;                         *(u32x2*)(ACT + (size_t)Rl * DFF + col) = ov;
;                         if (t >= Lq - 2) *(f32x4*)((smp ? stout_s : stout_p) + (size_t)((l * 16 + sq) * 2 + (t - (Lq - 2))) * DFF + col) = g4;
.LBB0_733:
	s_or_b64 exec, exec, s[2:3]
	s_and_saveexec_b64 s[2:3], s[46:47]
	s_cbranch_execz .LBB0_736
	s_waitcnt lgkmcnt(0)
	v_cmp_ge_u32_e32 vcc, v125, v127
	v_pk_mul_f32 v[112:113], v[88:89], v[112:113]
	v_pk_mul_f32 v[114:115], v[90:91], v[114:115]
	v_pk_fma_f32 v[112:113], v[92:93], v[108:109], v[112:113]
	v_pk_fma_f32 v[114:115], v[94:95], v[110:111], v[114:115]
	v_pk_fma_f32 v[112:113], v[96:97], v[100:101], v[112:113]
	v_pk_fma_f32 v[114:115], v[98:99], v[102:103], v[114:115]
	v_pk_mul_f32 v[108:109], v[112:113], s[98:99] op_sel_hi:[1,0]
	v_pk_mul_f32 v[110:111], v[114:115], s[98:99] op_sel_hi:[1,0]
	v_exp_f32_e32 v108, v108
	v_exp_f32_e32 v109, v109
	v_exp_f32_e32 v110, v110
	v_exp_f32_e32 v111, v111
	v_pk_add_f32 v[108:109], v[108:109], 1.0 op_sel_hi:[1,0]
	v_pk_add_f32 v[110:111], v[110:111], 1.0 op_sel_hi:[1,0]
	v_rcp_f32_e32 v108, v108
	v_rcp_f32_e32 v109, v109
	v_rcp_f32_e32 v110, v110
	v_rcp_f32_e32 v111, v111
	v_pk_mul_f32 v[112:113], v[112:113], v[108:109]
	v_pk_mul_f32 v[114:115], v[114:115], v[110:111]
	v_pk_mul_f32 v[104:105], v[104:105], v[112:113]
	v_pk_mul_f32 v[106:107], v[106:107], v[114:115]
	v_cvt_pk_bf16_f32 v104, v104, v105
	v_cvt_pk_bf16_f32 v105, v106, v107
	v_mov_b64_e32 v[106:107], s[56:57]
	v_mad_i64_i32 v[106:107], s[48:49], v122, s59, v[106:107]
	v_lshl_add_u64 v[106:107], v[172:173], 1, v[106:107]
	global_store_dwordx2 v[106:107], v[104:105], off
	s_and_b64 exec, exec, vcc
	s_cbranch_execz .LBB0_736
	v_readlane_b32 s21, v249, 51
	v_sub_u32_e32 v107, s96, v127
	s_nop 0
	v_mov_b32_e32 v104, s21
	v_readlane_b32 s21, v249, 53
	s_nop 1
	v_mov_b32_e32 v105, s21
	v_readlane_b32 s21, v249, 50
	v_cndmask_b32_e64 v105, v104, v105, s[94:95]
	s_nop 0
	v_mov_b32_e32 v104, s21
	v_readlane_b32 s21, v249, 52
	s_nop 1
	v_mov_b32_e32 v106, s21
	v_cndmask_b32_e64 v104, v104, v106, s[94:95]
	v_lshlrev_b32_e32 v106, 1, v126
	v_add3_u32 v106, v107, v106, v125
	v_mad_i64_i32 v[104:105], s[48:49], v106, s97, v[104:105]
	v_lshl_add_u64 v[104:105], v[172:173], 2, v[104:105]
	global_store_dwordx4 v[104:105], v[100:103], off

; __device__ __forceinline__ unsigned cvt_pk_bf16(float lo, float hi) { unsigned r; asm volatile("v_cvt_pk_bf16_f32 %0, %1, %2" : "=v"(r) : "v"(lo), "v"(hi)); return r; }
; __device__ __forceinline__ float fsigmoid(float x) { return __builtin_amdgcn_rcpf(1.f + __expf(-x)); }
;     __device__ __forceinline__ void operator()(const f32x4 (&acc)[2][2][4][2], const Unit& u, int wr, int wc, int fr, int fq) const {
;     ...
;                     if (valid) {
;                         const f32x4 v4 = acc[ai][1][m][n];
;                         float o[4];
; #pragma unroll
;                         for (int e = 0; e < 4; ++e) { const float y = w0[e] * p2[e] + w1[e] * p1[e] + w2[e] * g4[e]; o[e] = y * fsigmoid(y) * v4[e]; }
;                         u32x2 ov; ov.x = cvt_pk_bf16(o[0], o[1]); ov.y = cvt_pk_bf16(o[2], o[3]);
;                         *(u32x2*)(ACT + (size_t)Rl * DFF + col) = ov;
;                         if (t >= Lq - 2) *(f32x4*)((smp ? stout_s : stout_p) + (size_t)((l * 16 + sq) * 2 + (t - (Lq - 2))) * DFF + col) = g4;
.LBB0_744:
	s_or_b64 exec, exec, s[2:3]
	s_and_saveexec_b64 s[2:3], s[90:91]
	s_cbranch_execz .LBB0_747
	v_cmp_ge_u32_e32 vcc, v126, v128
	v_pk_mul_f32 v[106:107], v[88:89], v[106:107]
	v_pk_mul_f32 v[102:103], v[90:91], v[102:103]
	v_pk_fma_f32 v[106:107], v[92:93], v[104:105], v[106:107]
	v_pk_fma_f32 v[102:103], v[94:95], v[100:101], v[102:103]
	v_pk_fma_f32 v[106:107], v[96:97], v[80:81], v[106:107]
	v_pk_fma_f32 v[102:103], v[98:99], v[82:83], v[102:103]
	v_pk_mul_f32 v[104:105], v[106:107], s[98:99] op_sel_hi:[1,0]
	v_pk_mul_f32 v[100:101], v[102:103], s[98:99] op_sel_hi:[1,0]
	v_exp_f32_e32 v104, v104
	v_exp_f32_e32 v105, v105
	v_exp_f32_e32 v100, v100
	v_exp_f32_e32 v101, v101
	v_pk_add_f32 v[104:105], v[104:105], 1.0 op_sel_hi:[1,0]
	v_pk_add_f32 v[100:101], v[100:101], 1.0 op_sel_hi:[1,0]
	v_rcp_f32_e32 v104, v104
	v_rcp_f32_e32 v105, v105
	v_rcp_f32_e32 v100, v100
	v_rcp_f32_e32 v101, v101
	v_pk_mul_f32 v[106:107], v[106:107], v[104:105]
	v_pk_mul_f32 v[102:103], v[102:103], v[100:101]
	v_pk_mul_f32 v[84:85], v[84:85], v[106:107]
	v_pk_mul_f32 v[86:87], v[86:87], v[102:103]
	v_cvt_pk_bf16_f32 v84, v84, v85
	v_cvt_pk_bf16_f32 v85, v86, v87
	v_mov_b64_e32 v[86:87], s[56:57]
	v_mad_i64_i32 v[86:87], s[48:49], v118, s59, v[86:87]
	v_lshl_add_u64 v[86:87], v[172:173], 1, v[86:87]
	global_store_dwordx2 v[86:87], v[84:85], off
	s_and_b64 exec, exec, vcc
	s_cbranch_execz .LBB0_747
	v_readlane_b32 s21, v249, 51
	v_sub_u32_e32 v87, s96, v128
	s_nop 0
	v_mov_b32_e32 v84, s21
	v_readlane_b32 s21, v249, 53
	s_nop 1
	v_mov_b32_e32 v85, s21
	v_readlane_b32 s21, v249, 50
	v_cndmask_b32_e64 v85, v84, v85, s[30:31]
	s_nop 0
	v_mov_b32_e32 v84, s21
	v_readlane_b32 s21, v249, 52
	s_nop 1
	v_mov_b32_e32 v86, s21
	v_cndmask_b32_e64 v84, v84, v86, s[30:31]
	v_lshlrev_b32_e32 v86, 1, v127
	v_add3_u32 v86, v87, v86, v126
	v_mad_i64_i32 v[84:85], s[48:49], v86, s97, v[84:85]
	v_lshl_add_u64 v[84:85], v[172:173], 2, v[84:85]
	global_store_dwordx4 v[84:85], v[80:83], off

; __device__ __forceinline__ unsigned cvt_pk_bf16(float lo, float hi) { unsigned r; asm volatile("v_cvt_pk_bf16_f32 %0, %1, %2" : "=v"(r) : "v"(lo), "v"(hi)); return r; }
; __device__ __forceinline__ float fsigmoid(float x) { return __builtin_amdgcn_rcpf(1.f + __expf(-x)); }
;     __device__ __forceinline__ void operator()(const f32x4 (&acc)[2][2][4][2], const Unit& u, int wr, int wc, int fr, int fq) const {
;     ...
;                     if (valid) {
;                         const f32x4 v4 = acc[ai][1][m][n];
;                         float o[4];
; #pragma unroll
;                         for (int e = 0; e < 4; ++e) { const float y = w0[e] * p2[e] + w1[e] * p1[e] + w2[e] * g4[e]; o[e] = y * fsigmoid(y) * v4[e]; }
;                         u32x2 ov; ov.x = cvt_pk_bf16(o[0], o[1]); ov.y = cvt_pk_bf16(o[2], o[3]);
;                         *(u32x2*)(ACT + (size_t)Rl * DFF + col) = ov;
;                         if (t >= Lq - 2) *(f32x4*)((smp ? stout_s : stout_p) + (size_t)((l * 16 + sq) * 2 + (t - (Lq - 2))) * DFF + col) = g4;
.LBB0_755:
	s_or_b64 exec, exec, s[48:49]
	s_and_saveexec_b64 s[48:49], s[2:3]
	s_cbranch_execz .LBB0_758
	v_cmp_ge_u32_e32 vcc, v113, v115
	v_pk_mul_f32 v[86:87], v[88:89], v[86:87]
	v_pk_mul_f32 v[82:83], v[90:91], v[82:83]
	v_pk_fma_f32 v[86:87], v[92:93], v[84:85], v[86:87]
	v_pk_fma_f32 v[82:83], v[94:95], v[80:81], v[82:83]
	v_pk_fma_f32 v[86:87], v[96:97], v[72:73], v[86:87]
	v_pk_fma_f32 v[82:83], v[98:99], v[74:75], v[82:83]
	v_pk_mul_f32 v[84:85], v[86:87], s[98:99] op_sel_hi:[1,0]
	v_pk_mul_f32 v[80:81], v[82:83], s[98:99] op_sel_hi:[1,0]
	v_exp_f32_e32 v84, v84
	v_exp_f32_e32 v85, v85
	v_exp_f32_e32 v80, v80
	v_exp_f32_e32 v81, v81
	v_pk_add_f32 v[84:85], v[84:85], 1.0 op_sel_hi:[1,0]
	v_pk_add_f32 v[80:81], v[80:81], 1.0 op_sel_hi:[1,0]
	v_rcp_f32_e32 v84, v84
	v_rcp_f32_e32 v85, v85
	v_rcp_f32_e32 v80, v80
	v_rcp_f32_e32 v81, v81
	v_pk_mul_f32 v[86:87], v[86:87], v[84:85]
	v_pk_mul_f32 v[82:83], v[82:83], v[80:81]
	v_pk_mul_f32 v[76:77], v[76:77], v[86:87]
	v_pk_mul_f32 v[78:79], v[78:79], v[82:83]
	v_cvt_pk_bf16_f32 v76, v76, v77
	v_cvt_pk_bf16_f32 v77, v78, v79
	v_mov_b64_e32 v[78:79], s[56:57]
	v_mad_i64_i32 v[78:79], s[50:51], v110, s59, v[78:79]
	v_lshl_add_u64 v[78:79], v[172:173], 1, v[78:79]
	global_store_dwordx2 v[78:79], v[76:77], off
	s_and_b64 exec, exec, vcc
	s_cbranch_execz .LBB0_758
	v_readlane_b32 s21, v249, 51
	v_sub_u32_e32 v79, s96, v115
	s_nop 0
	v_mov_b32_e32 v76, s21
	v_readlane_b32 s21, v249, 53
	s_nop 1
	v_mov_b32_e32 v77, s21
	v_readlane_b32 s21, v249, 50
	v_cndmask_b32_e64 v77, v76, v77, s[36:37]
	s_nop 0
	v_mov_b32_e32 v76, s21
	v_readlane_b32 s21, v249, 52
	s_nop 1
	v_mov_b32_e32 v78, s21
	v_cndmask_b32_e64 v76, v76, v78, s[36:37]
	v_lshlrev_b32_e32 v78, 1, v114
	v_add3_u32 v78, v79, v78, v113
	v_mad_i64_i32 v[76:77], s[50:51], v78, s97, v[76:77]
	v_lshl_add_u64 v[76:77], v[172:173], 2, v[76:77]
	global_store_dwordx4 v[76:77], v[72:75], off

; __device__ __forceinline__ unsigned cvt_pk_bf16(float lo, float hi) { unsigned r; asm volatile("v_cvt_pk_bf16_f32 %0, %1, %2" : "=v"(r) : "v"(lo), "v"(hi)); return r; }
; __device__ __forceinline__ float fsigmoid(float x) { return __builtin_amdgcn_rcpf(1.f + __expf(-x)); }
;     __device__ __forceinline__ void operator()(const f32x4 (&acc)[2][2][4][2], const Unit& u, int wr, int wc, int fr, int fq) const {
;     ...
;                     if (valid) {
;                         const f32x4 v4 = acc[ai][1][m][n];
;                         float o[4];
; #pragma unroll
;                         for (int e = 0; e < 4; ++e) { const float y = w0[e] * p2[e] + w1[e] * p1[e] + w2[e] * g4[e]; o[e] = y * fsigmoid(y) * v4[e]; }
;                         u32x2 ov; ov.x = cvt_pk_bf16(o[0], o[1]); ov.y = cvt_pk_bf16(o[2], o[3]);
;                         *(u32x2*)(ACT + (size_t)Rl * DFF + col) = ov;
;                         if (t >= Lq - 2) *(f32x4*)((smp ? stout_s : stout_p) + (size_t)((l * 16 + sq) * 2 + (t - (Lq - 2))) * DFF + col) = g4;
.LBB0_766:
	s_or_b64 exec, exec, s[50:51]
	s_and_saveexec_b64 s[50:51], s[48:49]
	s_cbranch_execz .LBB0_769
	v_cmp_ge_u32_e32 vcc, v105, v107
	v_pk_mul_f32 v[78:79], v[88:89], v[78:79]
	v_pk_mul_f32 v[74:75], v[90:91], v[74:75]
	v_pk_fma_f32 v[78:79], v[92:93], v[76:77], v[78:79]
	v_pk_fma_f32 v[74:75], v[94:95], v[72:73], v[74:75]
	v_pk_fma_f32 v[78:79], v[96:97], v[64:65], v[78:79]
	v_pk_fma_f32 v[74:75], v[98:99], v[66:67], v[74:75]
	v_pk_mul_f32 v[76:77], v[78:79], s[98:99] op_sel_hi:[1,0]
	v_pk_mul_f32 v[72:73], v[74:75], s[98:99] op_sel_hi:[1,0]
	v_exp_f32_e32 v76, v76
	v_exp_f32_e32 v77, v77
	v_exp_f32_e32 v72, v72
	v_exp_f32_e32 v73, v73
	v_pk_add_f32 v[76:77], v[76:77], 1.0 op_sel_hi:[1,0]
	v_pk_add_f32 v[72:73], v[72:73], 1.0 op_sel_hi:[1,0]
	v_rcp_f32_e32 v76, v76
	v_rcp_f32_e32 v77, v77
	v_rcp_f32_e32 v72, v72
	v_rcp_f32_e32 v73, v73
	v_pk_mul_f32 v[78:79], v[78:79], v[76:77]
	v_pk_mul_f32 v[74:75], v[74:75], v[72:73]
	v_pk_mul_f32 v[68:69], v[68:69], v[78:79]
	v_pk_mul_f32 v[70:71], v[70:71], v[74:75]
	v_cvt_pk_bf16_f32 v68, v68, v69
	v_cvt_pk_bf16_f32 v69, v70, v71
	v_mov_b64_e32 v[70:71], s[56:57]
	v_mad_i64_i32 v[70:71], s[52:53], v102, s59, v[70:71]
	v_lshl_add_u64 v[70:71], v[172:173], 1, v[70:71]
	global_store_dwordx2 v[70:71], v[68:69], off
	s_and_b64 exec, exec, vcc
	s_cbranch_execz .LBB0_769
	v_readlane_b32 s21, v249, 51
	v_sub_u32_e32 v71, s96, v107
	s_nop 0
	v_mov_b32_e32 v68, s21
	v_readlane_b32 s21, v249, 53
	s_nop 1
	v_mov_b32_e32 v69, s21
	v_readlane_b32 s21, v249, 50
	v_cndmask_b32_e64 v69, v68, v69, s[72:73]
	s_nop 0
	v_mov_b32_e32 v68, s21
	v_readlane_b32 s21, v249, 52
	s_nop 1
	v_mov_b32_e32 v70, s21
	v_cndmask_b32_e64 v68, v68, v70, s[72:73]
	v_lshlrev_b32_e32 v70, 1, v106
	v_add3_u32 v70, v71, v70, v105
	v_mad_i64_i32 v[68:69], s[52:53], v70, s97, v[68:69]
	v_lshl_add_u64 v[68:69], v[172:173], 2, v[68:69]
	global_store_dwordx4 v[68:69], v[64:67], off

; __device__ __forceinline__ unsigned cvt_pk_bf16(float lo, float hi) { unsigned r; asm volatile("v_cvt_pk_bf16_f32 %0, %1, %2" : "=v"(r) : "v"(lo), "v"(hi)); return r; }
; __device__ __forceinline__ float fsigmoid(float x) { return __builtin_amdgcn_rcpf(1.f + __expf(-x)); }
;     __device__ __forceinline__ void operator()(const f32x4 (&acc)[2][2][4][2], const Unit& u, int wr, int wc, int fr, int fq) const {
;     ...
;                     if (valid) {
;                         const f32x4 v4 = acc[ai][1][m][n];
;                         float o[4];
; #pragma unroll
;                         for (int e = 0; e < 4; ++e) { const float y = w0[e] * p2[e] + w1[e] * p1[e] + w2[e] * g4[e]; o[e] = y * fsigmoid(y) * v4[e]; }
;                         u32x2 ov; ov.x = cvt_pk_bf16(o[0], o[1]); ov.y = cvt_pk_bf16(o[2], o[3]);
;                         *(u32x2*)(ACT + (size_t)Rl * DFF + col) = ov;
;                         if (t >= Lq - 2) *(f32x4*)((smp ? stout_s : stout_p) + (size_t)((l * 16 + sq) * 2 + (t - (Lq - 2))) * DFF + col) = g4;
.LBB0_781:
	s_or_b64 exec, exec, s[50:51]
	s_and_saveexec_b64 s[50:51], s[10:11]
	s_cbranch_execz .LBB0_784
	s_waitcnt lgkmcnt(0)
	v_cmp_ge_u32_e32 vcc, v188, v88
	v_pk_mul_f32 v[80:81], v[64:65], v[80:81]
	v_pk_mul_f32 v[82:83], v[66:67], v[82:83]
	v_pk_fma_f32 v[80:81], v[68:69], v[76:77], v[80:81]
	v_pk_fma_f32 v[82:83], v[70:71], v[78:79], v[82:83]
	v_pk_fma_f32 v[80:81], v[72:73], v[56:57], v[80:81]
	v_pk_fma_f32 v[82:83], v[74:75], v[58:59], v[82:83]
	v_pk_mul_f32 v[76:77], v[80:81], s[98:99] op_sel_hi:[1,0]
	v_pk_mul_f32 v[78:79], v[82:83], s[98:99] op_sel_hi:[1,0]
	v_exp_f32_e32 v76, v76
	v_exp_f32_e32 v77, v77
	v_exp_f32_e32 v78, v78
	v_exp_f32_e32 v79, v79
	v_pk_add_f32 v[76:77], v[76:77], 1.0 op_sel_hi:[1,0]
	v_pk_add_f32 v[78:79], v[78:79], 1.0 op_sel_hi:[1,0]
	v_rcp_f32_e32 v76, v76
	v_rcp_f32_e32 v77, v77
	v_rcp_f32_e32 v78, v78
	v_rcp_f32_e32 v79, v79
	v_pk_mul_f32 v[80:81], v[80:81], v[76:77]
	v_pk_mul_f32 v[82:83], v[82:83], v[78:79]
	v_pk_mul_f32 v[60:61], v[60:61], v[80:81]
	v_pk_mul_f32 v[62:63], v[62:63], v[82:83]
	v_cvt_pk_bf16_f32 v60, v60, v61
	v_cvt_pk_bf16_f32 v61, v62, v63
	v_mov_b64_e32 v[62:63], s[56:57]
	v_mad_i64_i32 v[62:63], s[10:11], v190, s59, v[62:63]
	v_lshl_add_u64 v[62:63], v[172:173], 1, v[62:63]
	global_store_dwordx2 v[62:63], v[60:61], off offset:8
	s_and_b64 exec, exec, vcc
	s_cbranch_execz .LBB0_784
	v_readlane_b32 s10, v249, 51
	v_sub_u32_e32 v63, s96, v88
	s_nop 0
	v_mov_b32_e32 v60, s10
	v_readlane_b32 s10, v249, 53
	s_nop 1
	v_mov_b32_e32 v61, s10
	v_readlane_b32 s10, v249, 50
	v_cndmask_b32_e64 v61, v60, v61, s[44:45]
	s_nop 0
	v_mov_b32_e32 v60, s10
	v_readlane_b32 s10, v249, 52
	s_nop 1
	v_mov_b32_e32 v62, s10
	v_cndmask_b32_e64 v60, v60, v62, s[44:45]
	v_lshlrev_b32_e32 v62, 1, v189
	v_add3_u32 v62, v63, v62, v188
	v_mad_i64_i32 v[60:61], s[10:11], v62, s97, v[60:61]
	v_lshl_add_u64 v[60:61], v[172:173], 2, v[60:61]
	global_store_dwordx4 v[60:61], v[56:59], off offset:16

; __device__ __forceinline__ unsigned cvt_pk_bf16(float lo, float hi) { unsigned r; asm volatile("v_cvt_pk_bf16_f32 %0, %1, %2" : "=v"(r) : "v"(lo), "v"(hi)); return r; }
; __device__ __forceinline__ float fsigmoid(float x) { return __builtin_amdgcn_rcpf(1.f + __expf(-x)); }
;     __device__ __forceinline__ void operator()(const f32x4 (&acc)[2][2][4][2], const Unit& u, int wr, int wc, int fr, int fq) const {
;     ...
;                     if (valid) {
;                         const f32x4 v4 = acc[ai][1][m][n];
;                         float o[4];
; #pragma unroll
;                         for (int e = 0; e < 4; ++e) { const float y = w0[e] * p2[e] + w1[e] * p1[e] + w2[e] * g4[e]; o[e] = y * fsigmoid(y) * v4[e]; }
;                         u32x2 ov; ov.x = cvt_pk_bf16(o[0], o[1]); ov.y = cvt_pk_bf16(o[2], o[3]);
;                         *(u32x2*)(ACT + (size_t)Rl * DFF + col) = ov;
;                         if (t >= Lq - 2) *(f32x4*)((smp ? stout_s : stout_p) + (size_t)((l * 16 + sq) * 2 + (t - (Lq - 2))) * DFF + col) = g4;
.LBB0_792:
	s_or_b64 exec, exec, s[10:11]
	s_and_saveexec_b64 s[10:11], s[0:1]
	s_cbranch_execz .LBB0_795
	v_cmp_ge_u32_e32 vcc, v148, v84
	v_pk_mul_f32 v[62:63], v[64:65], v[62:63]
	v_pk_mul_f32 v[58:59], v[66:67], v[58:59]
	v_pk_fma_f32 v[62:63], v[68:69], v[60:61], v[62:63]
	v_pk_fma_f32 v[58:59], v[70:71], v[56:57], v[58:59]
	v_pk_fma_f32 v[62:63], v[72:73], v[48:49], v[62:63]
	v_pk_fma_f32 v[58:59], v[74:75], v[50:51], v[58:59]
	v_pk_mul_f32 v[60:61], v[62:63], s[98:99] op_sel_hi:[1,0]
	v_pk_mul_f32 v[56:57], v[58:59], s[98:99] op_sel_hi:[1,0]
	v_exp_f32_e32 v60, v60
	v_exp_f32_e32 v61, v61
	v_exp_f32_e32 v56, v56
	v_exp_f32_e32 v57, v57
	v_pk_add_f32 v[60:61], v[60:61], 1.0 op_sel_hi:[1,0]
	v_pk_add_f32 v[56:57], v[56:57], 1.0 op_sel_hi:[1,0]
	v_rcp_f32_e32 v60, v60
	v_rcp_f32_e32 v61, v61
	v_rcp_f32_e32 v56, v56
	v_rcp_f32_e32 v57, v57
	v_pk_mul_f32 v[62:63], v[62:63], v[60:61]
	v_pk_mul_f32 v[58:59], v[58:59], v[56:57]
	v_pk_mul_f32 v[52:53], v[52:53], v[62:63]
	v_pk_mul_f32 v[54:55], v[54:55], v[58:59]
	v_cvt_pk_bf16_f32 v52, v52, v53
	v_cvt_pk_bf16_f32 v53, v54, v55
	v_mov_b64_e32 v[54:55], s[56:57]
	v_mad_i64_i32 v[54:55], s[0:1], v150, s59, v[54:55]
	v_lshl_add_u64 v[54:55], v[172:173], 1, v[54:55]
	global_store_dwordx2 v[54:55], v[52:53], off offset:8
	s_and_b64 exec, exec, vcc
	s_cbranch_execz .LBB0_795
	v_readlane_b32 s0, v249, 51
	v_sub_u32_e32 v55, s96, v84
	s_nop 0
	v_mov_b32_e32 v52, s0
	v_readlane_b32 s0, v249, 53
	s_nop 1
	v_mov_b32_e32 v53, s0
	v_readlane_b32 s0, v249, 50
	v_cndmask_b32_e64 v53, v52, v53, s[16:17]
	s_nop 0
	v_mov_b32_e32 v52, s0
	v_readlane_b32 s0, v249, 52
	s_nop 1
	v_mov_b32_e32 v54, s0
	v_cndmask_b32_e64 v52, v52, v54, s[16:17]
	v_lshlrev_b32_e32 v54, 1, v149
	v_add3_u32 v54, v55, v54, v148
	v_mad_i64_i32 v[52:53], s[0:1], v54, s97, v[52:53]
	v_lshl_add_u64 v[52:53], v[172:173], 2, v[52:53]
	global_store_dwordx4 v[52:53], v[48:51], off offset:16

; __device__ __forceinline__ unsigned cvt_pk_bf16(float lo, float hi) { unsigned r; asm volatile("v_cvt_pk_bf16_f32 %0, %1, %2" : "=v"(r) : "v"(lo), "v"(hi)); return r; }
; __device__ __forceinline__ float fsigmoid(float x) { return __builtin_amdgcn_rcpf(1.f + __expf(-x)); }
;     __device__ __forceinline__ void operator()(const f32x4 (&acc)[2][2][4][2], const Unit& u, int wr, int wc, int fr, int fq) const {
;     ...
;                     if (valid) {
;                         const f32x4 v4 = acc[ai][1][m][n];
;                         float o[4];
; #pragma unroll
;                         for (int e = 0; e < 4; ++e) { const float y = w0[e] * p2[e] + w1[e] * p1[e] + w2[e] * g4[e]; o[e] = y * fsigmoid(y) * v4[e]; }
;                         u32x2 ov; ov.x = cvt_pk_bf16(o[0], o[1]); ov.y = cvt_pk_bf16(o[2], o[3]);
;                         *(u32x2*)(ACT + (size_t)Rl * DFF + col) = ov;
;                         if (t >= Lq - 2) *(f32x4*)((smp ? stout_s : stout_p) + (size_t)((l * 16 + sq) * 2 + (t - (Lq - 2))) * DFF + col) = g4;
.LBB0_803:
	s_or_b64 exec, exec, s[0:1]
	s_and_saveexec_b64 s[0:1], s[8:9]
	s_cbranch_execz .LBB0_806
	v_cmp_ge_u32_e32 vcc, v140, v76
	v_pk_mul_f32 v[54:55], v[64:65], v[54:55]
	v_pk_mul_f32 v[50:51], v[66:67], v[50:51]
	v_pk_fma_f32 v[54:55], v[68:69], v[52:53], v[54:55]
	v_pk_fma_f32 v[50:51], v[70:71], v[48:49], v[50:51]
	v_pk_fma_f32 v[54:55], v[72:73], v[40:41], v[54:55]
	v_pk_fma_f32 v[50:51], v[74:75], v[42:43], v[50:51]
	v_pk_mul_f32 v[52:53], v[54:55], s[98:99] op_sel_hi:[1,0]
	v_pk_mul_f32 v[48:49], v[50:51], s[98:99] op_sel_hi:[1,0]
	v_exp_f32_e32 v52, v52
	v_exp_f32_e32 v53, v53
	v_exp_f32_e32 v48, v48
	v_exp_f32_e32 v49, v49
	v_pk_add_f32 v[52:53], v[52:53], 1.0 op_sel_hi:[1,0]
	v_pk_add_f32 v[48:49], v[48:49], 1.0 op_sel_hi:[1,0]
	v_rcp_f32_e32 v52, v52
	v_rcp_f32_e32 v53, v53
	v_rcp_f32_e32 v48, v48
	v_rcp_f32_e32 v49, v49
	v_pk_mul_f32 v[54:55], v[54:55], v[52:53]
	v_pk_mul_f32 v[50:51], v[50:51], v[48:49]
	v_pk_mul_f32 v[44:45], v[44:45], v[54:55]
	v_pk_mul_f32 v[46:47], v[46:47], v[50:51]
	v_cvt_pk_bf16_f32 v44, v44, v45
	v_cvt_pk_bf16_f32 v45, v46, v47
	v_mov_b64_e32 v[46:47], s[56:57]
	v_mad_i64_i32 v[46:47], s[8:9], v142, s59, v[46:47]
	v_lshl_add_u64 v[46:47], v[172:173], 1, v[46:47]
	global_store_dwordx2 v[46:47], v[44:45], off offset:8
	s_and_b64 exec, exec, vcc
	s_cbranch_execz .LBB0_806
	v_readlane_b32 s8, v249, 51
	v_sub_u32_e32 v47, s96, v76
	s_nop 0
	v_mov_b32_e32 v44, s8
	v_readlane_b32 s8, v249, 53
	s_nop 1
	v_mov_b32_e32 v45, s8
	v_readlane_b32 s8, v249, 50
	v_cndmask_b32_e64 v45, v44, v45, s[18:19]
	s_nop 0
	v_mov_b32_e32 v44, s8
	v_readlane_b32 s8, v249, 52
	s_nop 1
	v_mov_b32_e32 v46, s8
	v_cndmask_b32_e64 v44, v44, v46, s[18:19]
	v_lshlrev_b32_e32 v46, 1, v141
	v_add3_u32 v46, v47, v46, v140
	v_mad_i64_i32 v[44:45], s[8:9], v46, s97, v[44:45]
	v_lshl_add_u64 v[44:45], v[172:173], 2, v[44:45]
	global_store_dwordx4 v[44:45], v[40:43], off offset:16

; __device__ __forceinline__ unsigned cvt_pk_bf16(float lo, float hi) { unsigned r; asm volatile("v_cvt_pk_bf16_f32 %0, %1, %2" : "=v"(r) : "v"(lo), "v"(hi)); return r; }
; __device__ __forceinline__ float fsigmoid(float x) { return __builtin_amdgcn_rcpf(1.f + __expf(-x)); }
;     __device__ __forceinline__ void operator()(const f32x4 (&acc)[2][2][4][2], const Unit& u, int wr, int wc, int fr, int fq) const {
;     ...
;                     if (valid) {
;                         const f32x4 v4 = acc[ai][1][m][n];
;                         float o[4];
; #pragma unroll
;                         for (int e = 0; e < 4; ++e) { const float y = w0[e] * p2[e] + w1[e] * p1[e] + w2[e] * g4[e]; o[e] = y * fsigmoid(y) * v4[e]; }
;                         u32x2 ov; ov.x = cvt_pk_bf16(o[0], o[1]); ov.y = cvt_pk_bf16(o[2], o[3]);
;                         *(u32x2*)(ACT + (size_t)Rl * DFF + col) = ov;
;                         if (t >= Lq - 2) *(f32x4*)((smp ? stout_s : stout_p) + (size_t)((l * 16 + sq) * 2 + (t - (Lq - 2))) * DFF + col) = g4;
.LBB0_814:
	s_or_b64 exec, exec, s[0:1]
	s_and_saveexec_b64 s[0:1], s[12:13]
	s_cbranch_execz .LBB0_817
	v_cmp_ge_u32_e32 vcc, v132, v56
	v_pk_mul_f32 v[46:47], v[64:65], v[46:47]
	v_pk_mul_f32 v[42:43], v[66:67], v[42:43]
	v_pk_fma_f32 v[46:47], v[68:69], v[44:45], v[46:47]
	v_pk_fma_f32 v[42:43], v[70:71], v[40:41], v[42:43]
	v_pk_fma_f32 v[46:47], v[72:73], v[32:33], v[46:47]
	v_pk_fma_f32 v[42:43], v[74:75], v[34:35], v[42:43]
	v_pk_mul_f32 v[44:45], v[46:47], s[98:99] op_sel_hi:[1,0]
	v_pk_mul_f32 v[40:41], v[42:43], s[98:99] op_sel_hi:[1,0]
	v_exp_f32_e32 v44, v44
	v_exp_f32_e32 v45, v45
	v_exp_f32_e32 v40, v40
	v_exp_f32_e32 v41, v41
	v_pk_add_f32 v[44:45], v[44:45], 1.0 op_sel_hi:[1,0]
	v_pk_add_f32 v[40:41], v[40:41], 1.0 op_sel_hi:[1,0]
	v_rcp_f32_e32 v44, v44
	v_rcp_f32_e32 v45, v45
	v_rcp_f32_e32 v40, v40
	v_rcp_f32_e32 v41, v41
	v_pk_mul_f32 v[46:47], v[46:47], v[44:45]
	v_pk_mul_f32 v[42:43], v[42:43], v[40:41]
	v_pk_mul_f32 v[36:37], v[36:37], v[46:47]
	v_pk_mul_f32 v[38:39], v[38:39], v[42:43]
	v_cvt_pk_bf16_f32 v36, v36, v37
	v_cvt_pk_bf16_f32 v37, v38, v39
	v_mov_b64_e32 v[38:39], s[56:57]
	v_mad_i64_i32 v[38:39], s[8:9], v134, s59, v[38:39]
	v_lshl_add_u64 v[38:39], v[172:173], 1, v[38:39]
	global_store_dwordx2 v[38:39], v[36:37], off offset:8
	s_and_b64 exec, exec, vcc
	s_cbranch_execz .LBB0_817
	v_readlane_b32 s8, v249, 51
	v_sub_u32_e32 v39, s96, v56
	s_nop 0
	v_mov_b32_e32 v36, s8
	v_readlane_b32 s8, v249, 53
	s_nop 1
	v_mov_b32_e32 v37, s8
	v_readlane_b32 s8, v249, 50
	v_cndmask_b32_e64 v37, v36, v37, s[92:93]
	s_nop 0
	v_mov_b32_e32 v36, s8
	v_readlane_b32 s8, v249, 52
	s_nop 1
	v_mov_b32_e32 v38, s8
	v_cndmask_b32_e64 v36, v36, v38, s[92:93]
	v_lshlrev_b32_e32 v38, 1, v133
	v_add3_u32 v38, v39, v38, v132
	v_mad_i64_i32 v[36:37], s[8:9], v38, s97, v[36:37]
	v_lshl_add_u64 v[36:37], v[172:173], 2, v[36:37]
	global_store_dwordx4 v[36:37], v[32:35], off offset:16

; __device__ __forceinline__ unsigned cvt_pk_bf16(float lo, float hi) { unsigned r; asm volatile("v_cvt_pk_bf16_f32 %0, %1, %2" : "=v"(r) : "v"(lo), "v"(hi)); return r; }
; __device__ __forceinline__ float fsigmoid(float x) { return __builtin_amdgcn_rcpf(1.f + __expf(-x)); }
;     __device__ __forceinline__ void operator()(const f32x4 (&acc)[2][2][4][2], const Unit& u, int wr, int wc, int fr, int fq) const {
;     ...
;                     if (valid) {
;                         const f32x4 v4 = acc[ai][1][m][n];
;                         float o[4];
; #pragma unroll
;                         for (int e = 0; e < 4; ++e) { const float y = w0[e] * p2[e] + w1[e] * p1[e] + w2[e] * g4[e]; o[e] = y * fsigmoid(y) * v4[e]; }
;                         u32x2 ov; ov.x = cvt_pk_bf16(o[0], o[1]); ov.y = cvt_pk_bf16(o[2], o[3]);
;                         *(u32x2*)(ACT + (size_t)Rl * DFF + col) = ov;
;                         if (t >= Lq - 2) *(f32x4*)((smp ? stout_s : stout_p) + (size_t)((l * 16 + sq) * 2 + (t - (Lq - 2))) * DFF + col) = g4;
.LBB0_829:
	s_or_b64 exec, exec, s[0:1]
	s_and_saveexec_b64 s[0:1], s[46:47]
	s_cbranch_execz .LBB0_832
	s_waitcnt lgkmcnt(0)
	v_cmp_ge_u32_e32 vcc, v120, v44
	v_pk_mul_f32 v[36:37], v[64:65], v[36:37]
	v_pk_mul_f32 v[38:39], v[66:67], v[38:39]
	v_pk_fma_f32 v[36:37], v[68:69], v[32:33], v[36:37]
	v_pk_fma_f32 v[38:39], v[70:71], v[34:35], v[38:39]
	v_pk_fma_f32 v[36:37], v[72:73], v[24:25], v[36:37]
	v_pk_fma_f32 v[38:39], v[74:75], v[26:27], v[38:39]
	v_pk_mul_f32 v[32:33], v[36:37], s[98:99] op_sel_hi:[1,0]
	v_pk_mul_f32 v[34:35], v[38:39], s[98:99] op_sel_hi:[1,0]
	v_exp_f32_e32 v32, v32
	v_exp_f32_e32 v33, v33
	v_exp_f32_e32 v34, v34
	v_exp_f32_e32 v35, v35
	v_pk_add_f32 v[32:33], v[32:33], 1.0 op_sel_hi:[1,0]
	v_pk_add_f32 v[34:35], v[34:35], 1.0 op_sel_hi:[1,0]
	v_rcp_f32_e32 v32, v32
	v_rcp_f32_e32 v33, v33
	v_rcp_f32_e32 v34, v34
	v_rcp_f32_e32 v35, v35
	v_pk_mul_f32 v[36:37], v[36:37], v[32:33]
	v_pk_mul_f32 v[38:39], v[38:39], v[34:35]
	v_pk_mul_f32 v[28:29], v[28:29], v[36:37]
	v_pk_mul_f32 v[30:31], v[30:31], v[38:39]
	v_cvt_pk_bf16_f32 v28, v28, v29
	v_cvt_pk_bf16_f32 v29, v30, v31
	v_mov_b64_e32 v[30:31], s[56:57]
	v_mad_i64_i32 v[30:31], s[8:9], v122, s59, v[30:31]
	v_lshl_add_u64 v[30:31], v[172:173], 1, v[30:31]
	global_store_dwordx2 v[30:31], v[28:29], off offset:8
	s_and_b64 exec, exec, vcc
	s_cbranch_execz .LBB0_832
	v_readlane_b32 s8, v249, 51
	v_sub_u32_e32 v31, s96, v44
	s_nop 0
	v_mov_b32_e32 v28, s8
	v_readlane_b32 s8, v249, 53
	s_nop 1
	v_mov_b32_e32 v29, s8
	v_readlane_b32 s8, v249, 50
	v_cndmask_b32_e64 v29, v28, v29, s[94:95]
	s_nop 0
	v_mov_b32_e32 v28, s8
	v_readlane_b32 s8, v249, 52
	s_nop 1
	v_mov_b32_e32 v30, s8
	v_cndmask_b32_e64 v28, v28, v30, s[94:95]
	v_lshlrev_b32_e32 v30, 1, v121
	v_add3_u32 v30, v31, v30, v120
	v_mad_i64_i32 v[28:29], s[8:9], v30, s97, v[28:29]
	v_lshl_add_u64 v[28:29], v[172:173], 2, v[28:29]
	global_store_dwordx4 v[28:29], v[24:27], off offset:16

; __device__ __forceinline__ unsigned cvt_pk_bf16(float lo, float hi) { unsigned r; asm volatile("v_cvt_pk_bf16_f32 %0, %1, %2" : "=v"(r) : "v"(lo), "v"(hi)); return r; }
; __device__ __forceinline__ float fsigmoid(float x) { return __builtin_amdgcn_rcpf(1.f + __expf(-x)); }
;     __device__ __forceinline__ void operator()(const f32x4 (&acc)[2][2][4][2], const Unit& u, int wr, int wc, int fr, int fq) const {
;     ...
;                     if (valid) {
;                         const f32x4 v4 = acc[ai][1][m][n];
;                         float o[4];
; #pragma unroll
;                         for (int e = 0; e < 4; ++e) { const float y = w0[e] * p2[e] + w1[e] * p1[e] + w2[e] * g4[e]; o[e] = y * fsigmoid(y) * v4[e]; }
;                         u32x2 ov; ov.x = cvt_pk_bf16(o[0], o[1]); ov.y = cvt_pk_bf16(o[2], o[3]);
;                         *(u32x2*)(ACT + (size_t)Rl * DFF + col) = ov;
;                         if (t >= Lq - 2) *(f32x4*)((smp ? stout_s : stout_p) + (size_t)((l * 16 + sq) * 2 + (t - (Lq - 2))) * DFF + col) = g4;
.LBB0_840:
	s_or_b64 exec, exec, s[0:1]
	s_and_saveexec_b64 s[0:1], s[90:91]
	s_cbranch_execz .LBB0_843
	v_cmp_ge_u32_e32 vcc, v116, v40
	v_pk_mul_f32 v[30:31], v[64:65], v[30:31]
	v_pk_mul_f32 v[26:27], v[66:67], v[26:27]
	v_pk_fma_f32 v[30:31], v[68:69], v[28:29], v[30:31]
	v_pk_fma_f32 v[26:27], v[70:71], v[24:25], v[26:27]
	v_pk_fma_f32 v[30:31], v[72:73], v[16:17], v[30:31]
	v_pk_fma_f32 v[26:27], v[74:75], v[18:19], v[26:27]
	v_pk_mul_f32 v[28:29], v[30:31], s[98:99] op_sel_hi:[1,0]
	v_pk_mul_f32 v[24:25], v[26:27], s[98:99] op_sel_hi:[1,0]
	v_exp_f32_e32 v28, v28
	v_exp_f32_e32 v29, v29
	v_exp_f32_e32 v24, v24
	v_exp_f32_e32 v25, v25
	v_pk_add_f32 v[28:29], v[28:29], 1.0 op_sel_hi:[1,0]
	v_pk_add_f32 v[24:25], v[24:25], 1.0 op_sel_hi:[1,0]
	v_rcp_f32_e32 v28, v28
	v_rcp_f32_e32 v29, v29
	v_rcp_f32_e32 v24, v24
	v_rcp_f32_e32 v25, v25
	v_pk_mul_f32 v[30:31], v[30:31], v[28:29]
	v_pk_mul_f32 v[26:27], v[26:27], v[24:25]
	v_pk_mul_f32 v[20:21], v[20:21], v[30:31]
	v_pk_mul_f32 v[22:23], v[22:23], v[26:27]
	v_cvt_pk_bf16_f32 v20, v20, v21
	v_cvt_pk_bf16_f32 v21, v22, v23
	v_mov_b64_e32 v[22:23], s[56:57]
	v_mad_i64_i32 v[22:23], s[8:9], v118, s59, v[22:23]
	v_lshl_add_u64 v[22:23], v[172:173], 1, v[22:23]
	global_store_dwordx2 v[22:23], v[20:21], off offset:8
	s_and_b64 exec, exec, vcc
	s_cbranch_execz .LBB0_843
	v_readlane_b32 s8, v249, 51
	v_sub_u32_e32 v23, s96, v40
	s_nop 0
	v_mov_b32_e32 v20, s8
	v_readlane_b32 s8, v249, 53
	s_nop 1
	v_mov_b32_e32 v21, s8
	v_readlane_b32 s8, v249, 50
	v_cndmask_b32_e64 v21, v20, v21, s[30:31]
	s_nop 0
	v_mov_b32_e32 v20, s8
	v_readlane_b32 s8, v249, 52
	s_nop 1
	v_mov_b32_e32 v22, s8
	v_cndmask_b32_e64 v20, v20, v22, s[30:31]
	v_lshlrev_b32_e32 v22, 1, v117
	v_add3_u32 v22, v23, v22, v116
	v_mad_i64_i32 v[20:21], s[8:9], v22, s97, v[20:21]
	v_lshl_add_u64 v[20:21], v[172:173], 2, v[20:21]
	global_store_dwordx4 v[20:21], v[16:19], off offset:16

; __device__ __forceinline__ unsigned cvt_pk_bf16(float lo, float hi) { unsigned r; asm volatile("v_cvt_pk_bf16_f32 %0, %1, %2" : "=v"(r) : "v"(lo), "v"(hi)); return r; }
; __device__ __forceinline__ float fsigmoid(float x) { return __builtin_amdgcn_rcpf(1.f + __expf(-x)); }
;     __device__ __forceinline__ void operator()(const f32x4 (&acc)[2][2][4][2], const Unit& u, int wr, int wc, int fr, int fq) const {
;     ...
;                     if (valid) {
;                         const f32x4 v4 = acc[ai][1][m][n];
;                         float o[4];
; #pragma unroll
;                         for (int e = 0; e < 4; ++e) { const float y = w0[e] * p2[e] + w1[e] * p1[e] + w2[e] * g4[e]; o[e] = y * fsigmoid(y) * v4[e]; }
;                         u32x2 ov; ov.x = cvt_pk_bf16(o[0], o[1]); ov.y = cvt_pk_bf16(o[2], o[3]);
;                         *(u32x2*)(ACT + (size_t)Rl * DFF + col) = ov;
;                         if (t >= Lq - 2) *(f32x4*)((smp ? stout_s : stout_p) + (size_t)((l * 16 + sq) * 2 + (t - (Lq - 2))) * DFF + col) = g4;
.LBB0_851:
	s_or_b64 exec, exec, s[0:1]
	s_and_saveexec_b64 s[0:1], s[2:3]
	s_cbranch_execz .LBB0_854
	v_cmp_ge_u32_e32 vcc, v108, v32
	v_pk_mul_f32 v[22:23], v[64:65], v[22:23]
	v_pk_mul_f32 v[18:19], v[66:67], v[18:19]
	v_pk_fma_f32 v[22:23], v[68:69], v[20:21], v[22:23]
	v_pk_fma_f32 v[18:19], v[70:71], v[16:17], v[18:19]
	v_pk_fma_f32 v[22:23], v[72:73], v[8:9], v[22:23]
	v_pk_fma_f32 v[18:19], v[74:75], v[10:11], v[18:19]
	v_pk_mul_f32 v[20:21], v[22:23], s[98:99] op_sel_hi:[1,0]
	v_pk_mul_f32 v[16:17], v[18:19], s[98:99] op_sel_hi:[1,0]
	v_exp_f32_e32 v20, v20
	v_exp_f32_e32 v21, v21
	v_exp_f32_e32 v16, v16
	v_exp_f32_e32 v17, v17
	v_pk_add_f32 v[20:21], v[20:21], 1.0 op_sel_hi:[1,0]
	v_pk_add_f32 v[16:17], v[16:17], 1.0 op_sel_hi:[1,0]
	v_rcp_f32_e32 v20, v20
	v_rcp_f32_e32 v21, v21
	v_rcp_f32_e32 v16, v16
	v_rcp_f32_e32 v17, v17
	v_pk_mul_f32 v[22:23], v[22:23], v[20:21]
	v_pk_mul_f32 v[18:19], v[18:19], v[16:17]
	v_pk_mul_f32 v[12:13], v[12:13], v[22:23]
	v_pk_mul_f32 v[14:15], v[14:15], v[18:19]
	v_cvt_pk_bf16_f32 v12, v12, v13
	v_cvt_pk_bf16_f32 v13, v14, v15
	v_mov_b64_e32 v[14:15], s[56:57]
	v_mad_i64_i32 v[14:15], s[2:3], v110, s59, v[14:15]
	v_lshl_add_u64 v[14:15], v[172:173], 1, v[14:15]
	global_store_dwordx2 v[14:15], v[12:13], off offset:8
	s_and_b64 exec, exec, vcc
	s_cbranch_execz .LBB0_854
	v_readlane_b32 s2, v249, 51
	v_sub_u32_e32 v15, s96, v32
	s_nop 0
	v_mov_b32_e32 v12, s2
	v_readlane_b32 s2, v249, 53
	s_nop 1
	v_mov_b32_e32 v13, s2
	v_readlane_b32 s2, v249, 50
	v_cndmask_b32_e64 v13, v12, v13, s[36:37]
	s_nop 0
	v_mov_b32_e32 v12, s2
	v_readlane_b32 s2, v249, 52
	s_nop 1
	v_mov_b32_e32 v14, s2
	v_cndmask_b32_e64 v12, v12, v14, s[36:37]
	v_lshlrev_b32_e32 v14, 1, v109
	v_add3_u32 v14, v15, v14, v108
	v_mad_i64_i32 v[12:13], s[2:3], v14, s97, v[12:13]
	v_lshl_add_u64 v[12:13], v[172:173], 2, v[12:13]
	global_store_dwordx4 v[12:13], v[8:11], off offset:16

; __device__ __forceinline__ unsigned cvt_pk_bf16(float lo, float hi) { unsigned r; asm volatile("v_cvt_pk_bf16_f32 %0, %1, %2" : "=v"(r) : "v"(lo), "v"(hi)); return r; }
; __device__ __forceinline__ float fsigmoid(float x) { return __builtin_amdgcn_rcpf(1.f + __expf(-x)); }
;     __device__ __forceinline__ void operator()(const f32x4 (&acc)[2][2][4][2], const Unit& u, int wr, int wc, int fr, int fq) const {
;     ...
;                     if (valid) {
;                         const f32x4 v4 = acc[ai][1][m][n];
;                         float o[4];
; #pragma unroll
;                         for (int e = 0; e < 4; ++e) { const float y = w0[e] * p2[e] + w1[e] * p1[e] + w2[e] * g4[e]; o[e] = y * fsigmoid(y) * v4[e]; }
;                         u32x2 ov; ov.x = cvt_pk_bf16(o[0], o[1]); ov.y = cvt_pk_bf16(o[2], o[3]);
;                         *(u32x2*)(ACT + (size_t)Rl * DFF + col) = ov;
;                         if (t >= Lq - 2) *(f32x4*)((smp ? stout_s : stout_p) + (size_t)((l * 16 + sq) * 2 + (t - (Lq - 2))) * DFF + col) = g4;
.LBB0_862:
	s_or_b64 exec, exec, s[0:1]
	s_and_saveexec_b64 s[0:1], s[48:49]
	s_cbranch_execz .LBB0_865
	v_cmp_ge_u32_e32 vcc, v100, v24
	v_pk_mul_f32 v[14:15], v[64:65], v[14:15]
	v_pk_mul_f32 v[10:11], v[66:67], v[10:11]
	v_pk_fma_f32 v[14:15], v[68:69], v[12:13], v[14:15]
	v_pk_fma_f32 v[10:11], v[70:71], v[8:9], v[10:11]
	v_pk_fma_f32 v[14:15], v[72:73], v[4:5], v[14:15]
	v_pk_fma_f32 v[10:11], v[74:75], v[6:7], v[10:11]
	v_pk_mul_f32 v[12:13], v[14:15], s[98:99] op_sel_hi:[1,0]
	v_pk_mul_f32 v[8:9], v[10:11], s[98:99] op_sel_hi:[1,0]
	v_exp_f32_e32 v12, v12
	v_exp_f32_e32 v13, v13
	v_exp_f32_e32 v8, v8
	v_exp_f32_e32 v9, v9
	v_pk_add_f32 v[12:13], v[12:13], 1.0 op_sel_hi:[1,0]
	v_pk_add_f32 v[8:9], v[8:9], 1.0 op_sel_hi:[1,0]
	v_rcp_f32_e32 v12, v12
	v_rcp_f32_e32 v13, v13
	v_rcp_f32_e32 v8, v8
	v_rcp_f32_e32 v9, v9
	v_pk_mul_f32 v[14:15], v[14:15], v[12:13]
	v_pk_mul_f32 v[10:11], v[10:11], v[8:9]
	v_pk_mul_f32 v[0:1], v[0:1], v[14:15]
	v_pk_mul_f32 v[2:3], v[2:3], v[10:11]
	v_cvt_pk_bf16_f32 v0, v0, v1
	v_cvt_pk_bf16_f32 v1, v2, v3
	v_mov_b64_e32 v[2:3], s[56:57]
	v_mad_i64_i32 v[2:3], s[2:3], v102, s59, v[2:3]
	v_lshl_add_u64 v[2:3], v[172:173], 1, v[2:3]
	global_store_dwordx2 v[2:3], v[0:1], off offset:8
	s_and_b64 exec, exec, vcc
	s_cbranch_execz .LBB0_865
	v_readlane_b32 s2, v249, 51
	v_sub_u32_e32 v3, s96, v24
	s_nop 0
	v_mov_b32_e32 v0, s2
	v_readlane_b32 s2, v249, 53
	s_nop 1
	v_mov_b32_e32 v1, s2
	v_readlane_b32 s2, v249, 50
	v_cndmask_b32_e64 v1, v0, v1, s[72:73]
	s_nop 0
	v_mov_b32_e32 v0, s2
	v_readlane_b32 s2, v249, 52
	s_nop 1
	v_mov_b32_e32 v2, s2
	v_cndmask_b32_e64 v0, v0, v2, s[72:73]
	v_lshlrev_b32_e32 v2, 1, v101
	v_add3_u32 v2, v3, v2, v100
	v_mad_i64_i32 v[0:1], s[2:3], v2, s97, v[0:1]
	v_lshl_add_u64 v[0:1], v[172:173], 2, v[0:1]
	global_store_dwordx4 v[0:1], v[4:7], off offset:16

; __global__ void __launch_bounds__(512, 2) fwd_megakernel(Args a) {
	.amdhsa_kernel _Z14fwd_megakernel4Args
		.amdhsa_group_segment_fixed_size 0
		.amdhsa_private_segment_fixed_size 0
		.amdhsa_kernarg_size 464
		.amdhsa_user_sgpr_count 2
		.amdhsa_user_sgpr_dispatch_ptr 0
		.amdhsa_user_sgpr_queue_ptr 0
		.amdhsa_user_sgpr_kernarg_segment_ptr 1
		.amdhsa_user_sgpr_dispatch_id 0
		.amdhsa_user_sgpr_kernarg_preload_length 0
		.amdhsa_user_sgpr_kernarg_preload_offset 0
		.amdhsa_user_sgpr_private_segment_size 0
		.amdhsa_uses_dynamic_stack 0
		.amdhsa_enable_private_segment 0
		.amdhsa_system_sgpr_workgroup_id_x 1
		.amdhsa_system_sgpr_workgroup_id_y 0
		.amdhsa_system_sgpr_workgroup_id_z 0
		.amdhsa_system_sgpr_workgroup_info 0
		.amdhsa_system_vgpr_workitem_id 2
		.amdhsa_next_free_vgpr 252
		.amdhsa_next_free_sgpr 100
		.amdhsa_accum_offset 252
		.amdhsa_reserve_vcc 1
		.amdhsa_float_round_mode_32 0
		.amdhsa_float_round_mode_16_64 0
		.amdhsa_float_denorm_mode_32 3
		.amdhsa_float_denorm_mode_16_64 3
		.amdhsa_dx10_clamp 1
		.amdhsa_ieee_mode 1
		.amdhsa_fp16_overflow 0
		.amdhsa_tg_split 0
		.amdhsa_exception_fp_ieee_invalid_op 0
		.amdhsa_exception_fp_denorm_src 0
		.amdhsa_exception_fp_ieee_div_zero 0
		.amdhsa_exception_fp_ieee_overflow 0
		.amdhsa_exception_fp_ieee_underflow 0
		.amdhsa_exception_fp_ieee_inexact 0
		.amdhsa_exception_int_div_zero 0
	.end_amdhsa_kernel

; __global__ void __launch_bounds__(512, 2) fwd_megakernel(Args a) {
amdhsa.kernels:
  - .agpr_count:     0
    .args:
      - .offset:         0
        .size:           208
        .value_kind:     by_value
      - .offset:         208
        .size:           4
        .value_kind:     hidden_block_count_x
      - .offset:         212
        .size:           4
        .value_kind:     hidden_block_count_y
      - .offset:         216
        .size:           4
        .value_kind:     hidden_block_count_z
      - .offset:         220
        .size:           2
        .value_kind:     hidden_group_size_x
      - .offset:         222
        .size:           2
        .value_kind:     hidden_group_size_y
      - .offset:         224
        .size:           2
        .value_kind:     hidden_group_size_z
      - .offset:         226
        .size:           2
        .value_kind:     hidden_remainder_x
      - .offset:         228
        .size:           2
        .value_kind:     hidden_remainder_y
      - .offset:         230
        .size:           2
        .value_kind:     hidden_remainder_z
      - .offset:         248
        .size:           8
        .value_kind:     hidden_global_offset_x
      - .offset:         256
        .size:           8
        .value_kind:     hidden_global_offset_y
      - .offset:         264
        .size:           8
        .value_kind:     hidden_global_offset_z
      - .offset:         272
        .size:           2
        .value_kind:     hidden_grid_dims
      - .offset:         296
        .size:           8
        .value_kind:     hidden_multigrid_sync_arg
      - .offset:         328
        .size:           4
        .value_kind:     hidden_dynamic_lds_size
    .group_segment_fixed_size: 0
    .kernarg_segment_align: 8
    .kernarg_segment_size: 464
    .language:       OpenCL C
    .language_version:
      - 2
      - 0
    .max_flat_workgroup_size: 512
    .name:           _Z14fwd_megakernel4Args
    .private_segment_fixed_size: 0
    .sgpr_count:     106
    .sgpr_spill_count: 336
    .symbol:         _Z14fwd_megakernel4Args.kd
    .uniform_work_group_size: 1
    .uses_dynamic_stack: false
    .vgpr_count:     252
    .vgpr_spill_count: 0
    .wavefront_size: 64
